# GEMM K-loops: 8 of 16 LDS-DMA loads per iteration use SGPR-base + 32-bit VGPR offset form (no per-DMA 64-bit VALU add)
# baseline (speedup 1.0000x reference)
; #define PG8_STAGE(bufoff, gbase, voff) do { _Pragma("unroll") for (int _i = 0; _i < 2; ++_i) \
;         __builtin_amdgcn_global_load_lds((const unsigned*)((const char*)(gbase) + (voff)[_i]), (LAS unsigned*)(lds + (bufoff) + ldsw + _i * 8192), 16, 0, 0); } while (0)
; #define PG8_LDA(dst, b, h) do { _Pragma("unroll") for (int m = 0; m < 4; ++m) _Pragma("unroll") for (int k = 0; k < 2; ++k) dst[m][k] = *(const LAS bf16x8*)(lds + PG8_SA(b, h) + aoff + m * 2048 + k * 1024); } while (0)
; #define PG8_LDB(dst, b, h) do { _Pragma("unroll") for (int n = 0; n < 2; ++n) _Pragma("unroll") for (int k = 0; k < 2; ++k) dst[n][k] = *(const LAS bf16x8*)(lds + PG8_SB(b, h) + boff + n * 2048 + k * 1024); } while (0)
; #define PG8_WAIT_V(n) asm volatile("s_waitcnt vmcnt(" #n ")" ::: "memory")
; #define PG8_WAIT_L(n) asm volatile("s_waitcnt lgkmcnt(" #n ")" ::: "memory")
; template <bool ALIGN_EPI, class Epi, class Sched>
; DEV void gemm_phase(LAS unsigned char* lds, const Gemm g, const Sched& S, const Epi& E) {
;     ...
;         for (int t = 0; t < nt; t += 2) {
;             const bool last = (t == nt - 2);
;             const char* a1 = cA + (size_t)(t + 1) * kstep;
;             const char* a2 = last ? nA : cA + (size_t)(t + 2) * kstep; const char* b2 = last ? nB : cB + (size_t)(t + 2) * kstep;
;             const char* a3 = a2 + kstep; const char* b3 = b2 + kstep;
;             PG8_LDB(B0, 0, 0); PG8_LDB(B1, 0, 1); PG8_SCHED; PG8_LDA(At, 0, 0); PG8_STAGE(PG8_SA(1, 1), a1 + hstepA, voffA);
;             PG8_WAIT_V(8); PG8_WAIT_L(0); PG8_BAR; PG8_MMA(0, 0, At, B0); PG8_MMA(0, 1, At, B1); PG8_BAR; PG8_SCHED;
;             PG8_LDA(At, 0, 1); PG8_STAGE(PG8_SB(0, 0), b2, voffB); PG8_STAGE(PG8_SB(0, 1), b2 + hstep, voffB); PG8_STAGE(PG8_SA(0, 0), a2, voffA);
;             PG8_WAIT_V(8); PG8_WAIT_L(0); PG8_BAR; PG8_MMA(1, 0, At, B0); PG8_MMA(1, 1, At, B1); PG8_BAR; PG8_SCHED;
;             PG8_LDB(B0, 1, 0); PG8_LDB(B1, 1, 1); PG8_SCHED; PG8_LDA(At, 1, 0); PG8_STAGE(PG8_SA(0, 1), a2 + hstepA, voffA);
;             PG8_WAIT_V(8); PG8_WAIT_L(0); PG8_BAR; PG8_MMA(0, 0, At, B0); PG8_MMA(0, 1, At, B1); PG8_BAR; PG8_SCHED;
;             PG8_LDA(At, 1, 1); PG8_STAGE(PG8_SB(1, 0), b3, voffB); PG8_STAGE(PG8_SB(1, 1), b3 + hstep, voffB); PG8_STAGE(PG8_SA(1, 0), a3, voffA);
;             PG8_WAIT_V(8); PG8_WAIT_L(0); PG8_BAR; PG8_MMA(1, 0, At, B0); PG8_MMA(1, 1, At, B1); PG8_BAR; PG8_SCHED;
.LBB0_28:
	s_add_u32 s6, s4, 0x100
	s_addc_u32 s7, s5, 0
	s_add_i32 s24, 0, 0x10000
	s_cmp_eq_u32 s49, 12
	s_cselect_b32 s93, s85, s7
	s_cselect_b32 s92, vcc_lo, s6
	s_cselect_b32 s91, s83, s48
	s_cselect_b32 s90, vcc_hi, s21
	s_add_i32 s25, 0, 0x14000
	v_add_u32_e32 v82, s24, v171
	s_waitcnt lgkmcnt(0)
	v_add_u32_e32 v158, s25, v171
	ds_read_b128 v[62:65], v82
	ds_read_b128 v[66:69], v82 offset:1024
	ds_read_b128 v[78:81], v82 offset:2048
	ds_read_b128 v[82:85], v82 offset:3072
	ds_read_b128 v[122:125], v158
	ds_read_b128 v[134:137], v158 offset:1024
	ds_read_b128 v[154:157], v158 offset:2048
	ds_read_b128 v[158:161], v158 offset:3072
	s_add_i32 m0, s12, 0xc000
	ds_read_b128 v[162:165], v230
	ds_read_b128 v[166:169], v230 offset:1024
	ds_read_b128 v[192:195], v230 offset:2048
	ds_read_b128 v[196:199], v230 offset:3072
	ds_read_b128 v[200:203], v230 offset:4096
	ds_read_b128 v[204:207], v230 offset:5120
	ds_read_b128 v[232:235], v230 offset:6144
	ds_read_b128 v[236:239], v230 offset:7168
	global_load_lds_dwordx4 v188, s[4:5]
	s_add_i32 m0, s12, 0xe000
	s_nop 0
	global_load_lds_dwordx4 v190, s[4:5]
	s_waitcnt vmcnt(8)
	s_waitcnt lgkmcnt(0)
	s_barrier
	s_setprio 1
	s_waitcnt lgkmcnt(0)
	v_mfma_f32_16x16x32_bf16 v[130:133], v[62:65], v[162:165], v[130:133]
	v_mfma_f32_16x16x32_bf16 v[118:121], v[78:81], v[162:165], v[118:121]
	v_mfma_f32_16x16x32_bf16 v[110:113], v[62:65], v[192:195], v[110:113]
	v_mfma_f32_16x16x32_bf16 v[102:105], v[78:81], v[192:195], v[102:105]
	v_mfma_f32_16x16x32_bf16 v[94:97], v[62:65], v[200:203], v[94:97]
	v_mfma_f32_16x16x32_bf16 v[86:89], v[78:81], v[200:203], v[86:89]
	v_mfma_f32_16x16x32_bf16 v[70:73], v[62:65], v[232:235], v[70:73]
	v_mfma_f32_16x16x32_bf16 v[54:57], v[78:81], v[232:235], v[54:57]
	v_mfma_f32_16x16x32_bf16 v[130:133], v[66:69], v[166:169], v[130:133]
	v_mfma_f32_16x16x32_bf16 v[118:121], v[82:85], v[166:169], v[118:121]
	v_mfma_f32_16x16x32_bf16 v[110:113], v[66:69], v[196:199], v[110:113]
	v_mfma_f32_16x16x32_bf16 v[102:105], v[82:85], v[196:199], v[102:105]
	v_mfma_f32_16x16x32_bf16 v[94:97], v[66:69], v[204:207], v[94:97]
	v_mfma_f32_16x16x32_bf16 v[86:89], v[82:85], v[204:207], v[86:89]
	v_mfma_f32_16x16x32_bf16 v[70:73], v[66:69], v[236:239], v[70:73]
	v_mfma_f32_16x16x32_bf16 v[54:57], v[82:85], v[236:239], v[54:57]
	s_setprio 0
	s_setprio 1
	v_mfma_f32_16x16x32_bf16 v[150:153], v[122:125], v[162:165], v[150:153]
	v_mfma_f32_16x16x32_bf16 v[146:149], v[154:157], v[162:165], v[146:149]
	v_mfma_f32_16x16x32_bf16 v[142:145], v[122:125], v[192:195], v[142:145]
	v_mfma_f32_16x16x32_bf16 v[138:141], v[154:157], v[192:195], v[138:141]
	v_mfma_f32_16x16x32_bf16 v[126:129], v[122:125], v[200:203], v[126:129]
	v_mfma_f32_16x16x32_bf16 v[114:117], v[154:157], v[200:203], v[114:117]
	v_mfma_f32_16x16x32_bf16 v[106:109], v[122:125], v[232:235], v[106:109]
	v_mfma_f32_16x16x32_bf16 v[98:101], v[154:157], v[232:235], v[98:101]
	v_mfma_f32_16x16x32_bf16 v[150:153], v[134:137], v[166:169], v[150:153]
	v_mfma_f32_16x16x32_bf16 v[146:149], v[158:161], v[166:169], v[146:149]
	v_mfma_f32_16x16x32_bf16 v[142:145], v[134:137], v[196:199], v[142:145]
	v_mfma_f32_16x16x32_bf16 v[138:141], v[158:161], v[196:199], v[138:141]
	v_mfma_f32_16x16x32_bf16 v[126:129], v[134:137], v[204:207], v[126:129]
	v_mfma_f32_16x16x32_bf16 v[114:117], v[158:161], v[204:207], v[114:117]
	v_mfma_f32_16x16x32_bf16 v[106:109], v[134:137], v[236:239], v[106:109]
	v_mfma_f32_16x16x32_bf16 v[98:101], v[158:161], v[236:239], v[98:101]
	s_setprio 0
	s_barrier
	s_add_i32 s4, s24, s8
	v_lshl_add_u64 v[208:209], s[90:91], 0, v[0:1]
	s_mov_b32 m0, s4
	ds_read_b128 v[162:165], v230 offset:16384
	ds_read_b128 v[166:169], v230 offset:17408
	ds_read_b128 v[192:195], v230 offset:18432
	ds_read_b128 v[196:199], v230 offset:19456
	ds_read_b128 v[200:203], v230 offset:20480
	ds_read_b128 v[204:207], v230 offset:21504
	ds_read_b128 v[232:235], v230 offset:22528
	ds_read_b128 v[236:239], v230 offset:23552
	global_load_lds_dwordx4 v[208:209], off
	s_add_i32 m0, s4, 0x2000
	s_add_u32 s4, s90, 0x40000
	v_lshl_add_u64 v[214:215], s[90:91], 0, v[180:181]
	s_addc_u32 s5, s91, 0
	s_add_i32 s24, s25, s8
	global_load_lds_dwordx4 v[214:215], off
	s_mov_b32 m0, s24
	v_lshl_add_u64 v[242:243], s[92:93], 0, v[182:183]
	global_load_lds_dwordx4 v0, s[4:5]
	s_add_i32 m0, s24, 0x2000
	s_nop 0
	global_load_lds_dwordx4 v180, s[4:5]
	v_lshl_add_u64 v[240:241], s[92:93], 0, v[184:185]
	s_mov_b32 m0, s12
	s_nop 0
	global_load_lds_dwordx4 v[240:241], off
	s_mov_b32 m0, s13
	s_nop 0
	global_load_lds_dwordx4 v[242:243], off
	s_waitcnt vmcnt(8)
	s_waitcnt lgkmcnt(0)
	s_barrier
; #define PG8_STAGE(bufoff, gbase, voff) do { _Pragma("unroll") for (int _i = 0; _i < 2; ++_i) \
;         __builtin_amdgcn_global_load_lds((const unsigned*)((const char*)(gbase) + (voff)[_i]), (LAS unsigned*)(lds + (bufoff) + ldsw + _i * 8192), 16, 0, 0); } while (0)
; #define PG8_LDA(dst, b, h) do { _Pragma("unroll") for (int m = 0; m < 4; ++m) _Pragma("unroll") for (int k = 0; k < 2; ++k) dst[m][k] = *(const LAS bf16x8*)(lds + PG8_SA(b, h) + aoff + m * 2048 + k * 1024); } while (0)
; #define PG8_LDB(dst, b, h) do { _Pragma("unroll") for (int n = 0; n < 2; ++n) _Pragma("unroll") for (int k = 0; k < 2; ++k) dst[n][k] = *(const LAS bf16x8*)(lds + PG8_SB(b, h) + boff + n * 2048 + k * 1024); } while (0)
; #define PG8_WAIT_V(n) asm volatile("s_waitcnt vmcnt(" #n ")" ::: "memory")
; #define PG8_WAIT_L(n) asm volatile("s_waitcnt lgkmcnt(" #n ")" ::: "memory")
; template <bool ALIGN_EPI, class Epi, class Sched>
; DEV void gemm_phase(LAS unsigned char* lds, const Gemm g, const Sched& S, const Epi& E) {
;     ...
;         for (int t = 0; t < nt; t += 2) {
;             const bool last = (t == nt - 2);
;             const char* a1 = cA + (size_t)(t + 1) * kstep;
;             const char* a2 = last ? nA : cA + (size_t)(t + 2) * kstep; const char* b2 = last ? nB : cB + (size_t)(t + 2) * kstep;
;             const char* a3 = a2 + kstep; const char* b3 = b2 + kstep;
;             PG8_LDB(B0, 0, 0); PG8_LDB(B1, 0, 1); PG8_SCHED; PG8_LDA(At, 0, 0); PG8_STAGE(PG8_SA(1, 1), a1 + hstepA, voffA);
;             PG8_WAIT_V(8); PG8_WAIT_L(0); PG8_BAR; PG8_MMA(0, 0, At, B0); PG8_MMA(0, 1, At, B1); PG8_BAR; PG8_SCHED;
;             PG8_LDA(At, 0, 1); PG8_STAGE(PG8_SB(0, 0), b2, voffB); PG8_STAGE(PG8_SB(0, 1), b2 + hstep, voffB); PG8_STAGE(PG8_SA(0, 0), a2, voffA);
;             PG8_WAIT_V(8); PG8_WAIT_L(0); PG8_BAR; PG8_MMA(1, 0, At, B0); PG8_MMA(1, 1, At, B1); PG8_BAR; PG8_SCHED;
;             PG8_LDB(B0, 1, 0); PG8_LDB(B1, 1, 1); PG8_SCHED; PG8_LDA(At, 1, 0); PG8_STAGE(PG8_SA(0, 1), a2 + hstepA, voffA);
;             PG8_WAIT_V(8); PG8_WAIT_L(0); PG8_BAR; PG8_MMA(0, 0, At, B0); PG8_MMA(0, 1, At, B1); PG8_BAR; PG8_SCHED;
;             PG8_LDA(At, 1, 1); PG8_STAGE(PG8_SB(1, 0), b3, voffB); PG8_STAGE(PG8_SB(1, 1), b3 + hstep, voffB); PG8_STAGE(PG8_SA(1, 0), a3, voffA);
;             PG8_WAIT_V(8); PG8_WAIT_L(0); PG8_BAR; PG8_MMA(1, 0, At, B0); PG8_MMA(1, 1, At, B1); PG8_BAR; PG8_SCHED;
	s_setprio 1
	s_waitcnt lgkmcnt(0)
	v_mfma_f32_16x16x32_bf16 v[46:49], v[62:65], v[162:165], v[46:49]
	v_mfma_f32_16x16x32_bf16 v[38:41], v[78:81], v[162:165], v[38:41]
	v_mfma_f32_16x16x32_bf16 v[30:33], v[62:65], v[192:195], v[30:33]
	v_mfma_f32_16x16x32_bf16 v[14:17], v[78:81], v[192:195], v[14:17]
	v_mfma_f32_16x16x32_bf16 v[26:29], v[62:65], v[200:203], v[26:29]
	v_mfma_f32_16x16x32_bf16 v[10:13], v[78:81], v[200:203], v[10:13]
	v_mfma_f32_16x16x32_bf16 v[22:25], v[62:65], v[232:235], v[22:25]
	v_mfma_f32_16x16x32_bf16 v[6:9], v[78:81], v[232:235], v[6:9]
	v_mfma_f32_16x16x32_bf16 v[46:49], v[66:69], v[166:169], v[46:49]
	v_mfma_f32_16x16x32_bf16 v[38:41], v[82:85], v[166:169], v[38:41]
	v_mfma_f32_16x16x32_bf16 v[30:33], v[66:69], v[196:199], v[30:33]
	v_mfma_f32_16x16x32_bf16 v[14:17], v[82:85], v[196:199], v[14:17]
	v_mfma_f32_16x16x32_bf16 v[26:29], v[66:69], v[204:207], v[26:29]
	v_mfma_f32_16x16x32_bf16 v[10:13], v[82:85], v[204:207], v[10:13]
	v_mfma_f32_16x16x32_bf16 v[22:25], v[66:69], v[236:239], v[22:25]
	v_mfma_f32_16x16x32_bf16 v[6:9], v[82:85], v[236:239], v[6:9]
	s_setprio 0
	s_setprio 1
	v_mfma_f32_16x16x32_bf16 v[58:61], v[122:125], v[192:195], v[58:61]
	v_mfma_f32_16x16x32_bf16 v[50:53], v[154:157], v[192:195], v[50:53]
	v_mfma_f32_16x16x32_bf16 v[42:45], v[122:125], v[200:203], v[42:45]
	v_mfma_f32_16x16x32_bf16 v[34:37], v[154:157], v[200:203], v[34:37]
	v_mfma_f32_16x16x32_bf16 v[18:21], v[122:125], v[232:235], v[18:21]
	v_mfma_f32_16x16x32_bf16 v[2:5], v[154:157], v[232:235], v[2:5]
	v_mfma_f32_16x16x32_bf16 v[62:65], v[122:125], v[162:165], v[90:93]
	v_mfma_f32_16x16x32_bf16 v[66:69], v[154:157], v[162:165], v[74:77]
	v_mfma_f32_16x16x32_bf16 v[58:61], v[134:137], v[196:199], v[58:61]
	v_mfma_f32_16x16x32_bf16 v[50:53], v[158:161], v[196:199], v[50:53]
	v_mfma_f32_16x16x32_bf16 v[42:45], v[134:137], v[204:207], v[42:45]
	v_mfma_f32_16x16x32_bf16 v[34:37], v[158:161], v[204:207], v[34:37]
	v_mfma_f32_16x16x32_bf16 v[18:21], v[134:137], v[236:239], v[18:21]
	v_mfma_f32_16x16x32_bf16 v[2:5], v[158:161], v[236:239], v[2:5]
	v_mfma_f32_16x16x32_bf16 v[62:65], v[134:137], v[166:169], v[62:65]
	v_mfma_f32_16x16x32_bf16 v[66:69], v[158:161], v[166:169], v[66:69]
	s_setprio 0
	s_barrier
	s_add_i32 s24, 0, 0x18000
	s_add_i32 s25, 0, 0x1c000
	v_add_u32_e32 v90, s24, v171
	v_add_u32_e32 v158, s25, v171
	ds_read_b128 v[74:77], v90
	ds_read_b128 v[78:81], v90 offset:1024
	ds_read_b128 v[82:85], v90 offset:2048
	ds_read_b128 v[90:93], v90 offset:3072
	ds_read_b128 v[122:125], v158
	ds_read_b128 v[134:137], v158 offset:1024
	ds_read_b128 v[154:157], v158 offset:2048
	ds_read_b128 v[158:161], v158 offset:3072
	s_add_u32 s4, s92, 0x2000
	s_addc_u32 s5, s93, 0
	s_mov_b32 m0, s15
	ds_read_b128 v[162:165], v230 offset:32768
	ds_read_b128 v[166:169], v230 offset:33792
	ds_read_b128 v[192:195], v230 offset:34816
	ds_read_b128 v[196:199], v230 offset:35840
	ds_read_b128 v[200:203], v230 offset:36864
	ds_read_b128 v[204:207], v230 offset:37888
	ds_read_b128 v[232:235], v230 offset:38912
	ds_read_b128 v[236:239], v230 offset:39936
	global_load_lds_dwordx4 v184, s[4:5]
	s_mov_b32 m0, s17
	s_nop 0
	global_load_lds_dwordx4 v182, s[4:5]
	s_waitcnt vmcnt(8)
	s_waitcnt lgkmcnt(0)
	s_barrier
	s_setprio 1
	s_waitcnt lgkmcnt(0)
	v_mfma_f32_16x16x32_bf16 v[130:133], v[74:77], v[162:165], v[130:133]
	v_mfma_f32_16x16x32_bf16 v[118:121], v[82:85], v[162:165], v[118:121]
	v_mfma_f32_16x16x32_bf16 v[110:113], v[74:77], v[192:195], v[110:113]
	v_mfma_f32_16x16x32_bf16 v[102:105], v[82:85], v[192:195], v[102:105]
	v_mfma_f32_16x16x32_bf16 v[94:97], v[74:77], v[200:203], v[94:97]
	v_mfma_f32_16x16x32_bf16 v[86:89], v[82:85], v[200:203], v[86:89]
	v_mfma_f32_16x16x32_bf16 v[70:73], v[74:77], v[232:235], v[70:73]
	v_mfma_f32_16x16x32_bf16 v[54:57], v[82:85], v[232:235], v[54:57]
	v_mfma_f32_16x16x32_bf16 v[130:133], v[78:81], v[166:169], v[130:133]
	v_mfma_f32_16x16x32_bf16 v[118:121], v[90:93], v[166:169], v[118:121]
	v_mfma_f32_16x16x32_bf16 v[110:113], v[78:81], v[196:199], v[110:113]
	v_mfma_f32_16x16x32_bf16 v[102:105], v[90:93], v[196:199], v[102:105]
	v_mfma_f32_16x16x32_bf16 v[94:97], v[78:81], v[204:207], v[94:97]
	v_mfma_f32_16x16x32_bf16 v[86:89], v[90:93], v[204:207], v[86:89]
	v_mfma_f32_16x16x32_bf16 v[70:73], v[78:81], v[236:239], v[70:73]
	v_mfma_f32_16x16x32_bf16 v[54:57], v[90:93], v[236:239], v[54:57]
	s_setprio 0
	s_setprio 1
	v_mfma_f32_16x16x32_bf16 v[150:153], v[122:125], v[162:165], v[150:153]
	v_mfma_f32_16x16x32_bf16 v[146:149], v[154:157], v[162:165], v[146:149]
	v_mfma_f32_16x16x32_bf16 v[142:145], v[122:125], v[192:195], v[142:145]
	v_mfma_f32_16x16x32_bf16 v[138:141], v[154:157], v[192:195], v[138:141]
	v_mfma_f32_16x16x32_bf16 v[126:129], v[122:125], v[200:203], v[126:129]
	v_mfma_f32_16x16x32_bf16 v[114:117], v[154:157], v[200:203], v[114:117]
	v_mfma_f32_16x16x32_bf16 v[106:109], v[122:125], v[232:235], v[106:109]
	v_mfma_f32_16x16x32_bf16 v[98:101], v[154:157], v[232:235], v[98:101]
	v_mfma_f32_16x16x32_bf16 v[150:153], v[134:137], v[166:169], v[150:153]
	v_mfma_f32_16x16x32_bf16 v[146:149], v[158:161], v[166:169], v[146:149]
	v_mfma_f32_16x16x32_bf16 v[142:145], v[134:137], v[196:199], v[142:145]
	v_mfma_f32_16x16x32_bf16 v[138:141], v[158:161], v[196:199], v[138:141]
	v_mfma_f32_16x16x32_bf16 v[126:129], v[134:137], v[204:207], v[126:129]
	v_mfma_f32_16x16x32_bf16 v[114:117], v[158:161], v[204:207], v[114:117]
	v_mfma_f32_16x16x32_bf16 v[106:109], v[134:137], v[236:239], v[106:109]
	v_mfma_f32_16x16x32_bf16 v[98:101], v[158:161], v[236:239], v[98:101]
	s_setprio 0
	s_barrier
; #define PG8_STAGE(bufoff, gbase, voff) do { _Pragma("unroll") for (int _i = 0; _i < 2; ++_i) \
;         __builtin_amdgcn_global_load_lds((const unsigned*)((const char*)(gbase) + (voff)[_i]), (LAS unsigned*)(lds + (bufoff) + ldsw + _i * 8192), 16, 0, 0); } while (0)
; #define PG8_LDA(dst, b, h) do { _Pragma("unroll") for (int m = 0; m < 4; ++m) _Pragma("unroll") for (int k = 0; k < 2; ++k) dst[m][k] = *(const LAS bf16x8*)(lds + PG8_SA(b, h) + aoff + m * 2048 + k * 1024); } while (0)
; #define PG8_LDB(dst, b, h) do { _Pragma("unroll") for (int n = 0; n < 2; ++n) _Pragma("unroll") for (int k = 0; k < 2; ++k) dst[n][k] = *(const LAS bf16x8*)(lds + PG8_SB(b, h) + boff + n * 2048 + k * 1024); } while (0)
; #define PG8_WAIT_V(n) asm volatile("s_waitcnt vmcnt(" #n ")" ::: "memory")
; #define PG8_WAIT_L(n) asm volatile("s_waitcnt lgkmcnt(" #n ")" ::: "memory")
; template <bool ALIGN_EPI, class Epi, class Sched>
; DEV void gemm_phase(LAS unsigned char* lds, const Gemm g, const Sched& S, const Epi& E) {
;     ...
;         for (int t = 0; t < nt; t += 2) {
;             const bool last = (t == nt - 2);
;             const char* a1 = cA + (size_t)(t + 1) * kstep;
;             const char* a2 = last ? nA : cA + (size_t)(t + 2) * kstep; const char* b2 = last ? nB : cB + (size_t)(t + 2) * kstep;
;             const char* a3 = a2 + kstep; const char* b3 = b2 + kstep;
;             PG8_LDB(B0, 0, 0); PG8_LDB(B1, 0, 1); PG8_SCHED; PG8_LDA(At, 0, 0); PG8_STAGE(PG8_SA(1, 1), a1 + hstepA, voffA);
;             PG8_WAIT_V(8); PG8_WAIT_L(0); PG8_BAR; PG8_MMA(0, 0, At, B0); PG8_MMA(0, 1, At, B1); PG8_BAR; PG8_SCHED;
;             PG8_LDA(At, 0, 1); PG8_STAGE(PG8_SB(0, 0), b2, voffB); PG8_STAGE(PG8_SB(0, 1), b2 + hstep, voffB); PG8_STAGE(PG8_SA(0, 0), a2, voffA);
;             PG8_WAIT_V(8); PG8_WAIT_L(0); PG8_BAR; PG8_MMA(1, 0, At, B0); PG8_MMA(1, 1, At, B1); PG8_BAR; PG8_SCHED;
;             PG8_LDB(B0, 1, 0); PG8_LDB(B1, 1, 1); PG8_SCHED; PG8_LDA(At, 1, 0); PG8_STAGE(PG8_SA(0, 1), a2 + hstepA, voffA);
;             PG8_WAIT_V(8); PG8_WAIT_L(0); PG8_BAR; PG8_MMA(0, 0, At, B0); PG8_MMA(0, 1, At, B1); PG8_BAR; PG8_SCHED;
;             PG8_LDA(At, 1, 1); PG8_STAGE(PG8_SB(1, 0), b3, voffB); PG8_STAGE(PG8_SB(1, 1), b3 + hstep, voffB); PG8_STAGE(PG8_SA(1, 0), a3, voffA);
;             PG8_WAIT_V(8); PG8_WAIT_L(0); PG8_BAR; PG8_MMA(1, 0, At, B0); PG8_MMA(1, 1, At, B1); PG8_BAR; PG8_SCHED;
	s_add_i32 s4, s24, s8
	v_lshl_add_u64 v[208:209], v[208:209], 0, s[30:31]
	s_mov_b32 m0, s4
	ds_read_b128 v[162:165], v230 offset:49152
	ds_read_b128 v[166:169], v230 offset:50176
	ds_read_b128 v[192:195], v230 offset:51200
	ds_read_b128 v[196:199], v230 offset:52224
	ds_read_b128 v[200:203], v230 offset:53248
	ds_read_b128 v[204:207], v230 offset:54272
	ds_read_b128 v[232:235], v230 offset:55296
	ds_read_b128 v[236:239], v230 offset:56320
	global_load_lds_dwordx4 v[208:209], off
	s_add_i32 m0, s4, 0x2000
	s_add_u32 s4, s90, 0x40080
	v_lshl_add_u64 v[208:209], v[214:215], 0, s[30:31]
	s_addc_u32 s5, s91, 0
	s_add_i32 s24, s25, s8
	global_load_lds_dwordx4 v[208:209], off
	s_mov_b32 m0, s24
	s_nop 0
	global_load_lds_dwordx4 v0, s[4:5]
	s_add_i32 m0, s24, 0x2000
	s_nop 0
	global_load_lds_dwordx4 v180, s[4:5]
	v_lshl_add_u64 v[208:209], v[240:241], 0, s[30:31]
	s_mov_b32 m0, s94
	s_nop 0
	global_load_lds_dwordx4 v[208:209], off
	v_lshl_add_u64 v[208:209], v[242:243], 0, s[30:31]
	s_mov_b32 m0, s95
	s_nop 0
	global_load_lds_dwordx4 v[208:209], off
	s_waitcnt vmcnt(8)
	s_waitcnt lgkmcnt(0)
	s_barrier
	s_setprio 1
	s_waitcnt lgkmcnt(0)
	v_mfma_f32_16x16x32_bf16 v[46:49], v[74:77], v[162:165], v[46:49]
	v_mfma_f32_16x16x32_bf16 v[38:41], v[82:85], v[162:165], v[38:41]
	v_mfma_f32_16x16x32_bf16 v[30:33], v[74:77], v[192:195], v[30:33]
	v_mfma_f32_16x16x32_bf16 v[14:17], v[82:85], v[192:195], v[14:17]
	v_mfma_f32_16x16x32_bf16 v[26:29], v[74:77], v[200:203], v[26:29]
	v_mfma_f32_16x16x32_bf16 v[10:13], v[82:85], v[200:203], v[10:13]
	v_mfma_f32_16x16x32_bf16 v[22:25], v[74:77], v[232:235], v[22:25]
	v_mfma_f32_16x16x32_bf16 v[6:9], v[82:85], v[232:235], v[6:9]
	v_mfma_f32_16x16x32_bf16 v[46:49], v[78:81], v[166:169], v[46:49]
	v_mfma_f32_16x16x32_bf16 v[38:41], v[90:93], v[166:169], v[38:41]
	v_mfma_f32_16x16x32_bf16 v[30:33], v[78:81], v[196:199], v[30:33]
	v_mfma_f32_16x16x32_bf16 v[14:17], v[90:93], v[196:199], v[14:17]
	v_mfma_f32_16x16x32_bf16 v[26:29], v[78:81], v[204:207], v[26:29]
	v_mfma_f32_16x16x32_bf16 v[10:13], v[90:93], v[204:207], v[10:13]
	v_mfma_f32_16x16x32_bf16 v[22:25], v[78:81], v[236:239], v[22:25]
	v_mfma_f32_16x16x32_bf16 v[6:9], v[90:93], v[236:239], v[6:9]
	s_setprio 0
	s_setprio 1
	v_mfma_f32_16x16x32_bf16 v[62:65], v[122:125], v[162:165], v[62:65]
	v_mfma_f32_16x16x32_bf16 v[90:93], v[134:137], v[166:169], v[62:65]
	v_mfma_f32_16x16x32_bf16 v[62:65], v[154:157], v[162:165], v[66:69]
	v_mfma_f32_16x16x32_bf16 v[58:61], v[122:125], v[192:195], v[58:61]
	v_mfma_f32_16x16x32_bf16 v[50:53], v[154:157], v[192:195], v[50:53]
	v_mfma_f32_16x16x32_bf16 v[42:45], v[122:125], v[200:203], v[42:45]
	v_mfma_f32_16x16x32_bf16 v[34:37], v[154:157], v[200:203], v[34:37]
	v_mfma_f32_16x16x32_bf16 v[18:21], v[122:125], v[232:235], v[18:21]
	v_mfma_f32_16x16x32_bf16 v[2:5], v[154:157], v[232:235], v[2:5]
	v_mfma_f32_16x16x32_bf16 v[74:77], v[158:161], v[166:169], v[62:65]
	v_mfma_f32_16x16x32_bf16 v[58:61], v[134:137], v[196:199], v[58:61]
	v_mfma_f32_16x16x32_bf16 v[50:53], v[158:161], v[196:199], v[50:53]
	v_mfma_f32_16x16x32_bf16 v[42:45], v[134:137], v[204:207], v[42:45]
	v_mfma_f32_16x16x32_bf16 v[34:37], v[158:161], v[204:207], v[34:37]
	v_mfma_f32_16x16x32_bf16 v[18:21], v[134:137], v[236:239], v[18:21]
	v_mfma_f32_16x16x32_bf16 v[2:5], v[158:161], v[236:239], v[2:5]
	s_setprio 0
	s_barrier
	s_add_i32 s49, s49, 2
	s_add_u32 s21, s21, 0x100
	s_addc_u32 s48, s48, 0
	s_cmp_gt_u32 s49, 13
	s_mov_b64 s[4:5], s[6:7]
	s_cbranch_scc0 .LBB0_28
	s_and_b64 vcc, exec, s[52:53]
	s_cbranch_vccz .LBB0_31
	s_barrier

; #define PG8_STAGE(bufoff, gbase, voff) do { _Pragma("unroll") for (int _i = 0; _i < 2; ++_i) \
;         __builtin_amdgcn_global_load_lds((const unsigned*)((const char*)(gbase) + (voff)[_i]), (LAS unsigned*)(lds + (bufoff) + ldsw + _i * 8192), 16, 0, 0); } while (0)
; #define PG8_LDA(dst, b, h) do { _Pragma("unroll") for (int m = 0; m < 4; ++m) _Pragma("unroll") for (int k = 0; k < 2; ++k) dst[m][k] = *(const LAS bf16x8*)(lds + PG8_SA(b, h) + aoff + m * 2048 + k * 1024); } while (0)
; #define PG8_LDB(dst, b, h) do { _Pragma("unroll") for (int n = 0; n < 2; ++n) _Pragma("unroll") for (int k = 0; k < 2; ++k) dst[n][k] = *(const LAS bf16x8*)(lds + PG8_SB(b, h) + boff + n * 2048 + k * 1024); } while (0)
; #define PG8_WAIT_V(n) asm volatile("s_waitcnt vmcnt(" #n ")" ::: "memory")
; #define PG8_WAIT_L(n) asm volatile("s_waitcnt lgkmcnt(" #n ")" ::: "memory")
; template <bool ALIGN_EPI, class Epi, class Sched>
; DEV void gemm_phase(LAS unsigned char* lds, const Gemm g, const Sched& S, const Epi& E) {
;     ...
;         for (int t = 0; t < nt; t += 2) {
;             const bool last = (t == nt - 2);
;             const char* a1 = cA + (size_t)(t + 1) * kstep;
;             const char* a2 = last ? nA : cA + (size_t)(t + 2) * kstep; const char* b2 = last ? nB : cB + (size_t)(t + 2) * kstep;
;             const char* a3 = a2 + kstep; const char* b3 = b2 + kstep;
;             PG8_LDB(B0, 0, 0); PG8_LDB(B1, 0, 1); PG8_SCHED; PG8_LDA(At, 0, 0); PG8_STAGE(PG8_SA(1, 1), a1 + hstepA, voffA);
;             PG8_WAIT_V(8); PG8_WAIT_L(0); PG8_BAR; PG8_MMA(0, 0, At, B0); PG8_MMA(0, 1, At, B1); PG8_BAR; PG8_SCHED;
;             PG8_LDA(At, 0, 1); PG8_STAGE(PG8_SB(0, 0), b2, voffB); PG8_STAGE(PG8_SB(0, 1), b2 + hstep, voffB); PG8_STAGE(PG8_SA(0, 0), a2, voffA);
;             PG8_WAIT_V(8); PG8_WAIT_L(0); PG8_BAR; PG8_MMA(1, 0, At, B0); PG8_MMA(1, 1, At, B1); PG8_BAR; PG8_SCHED;
;             PG8_LDB(B0, 1, 0); PG8_LDB(B1, 1, 1); PG8_SCHED; PG8_LDA(At, 1, 0); PG8_STAGE(PG8_SA(0, 1), a2 + hstepA, voffA);
;             PG8_WAIT_V(8); PG8_WAIT_L(0); PG8_BAR; PG8_MMA(0, 0, At, B0); PG8_MMA(0, 1, At, B1); PG8_BAR; PG8_SCHED;
;             PG8_LDA(At, 1, 1); PG8_STAGE(PG8_SB(1, 0), b3, voffB); PG8_STAGE(PG8_SB(1, 1), b3 + hstep, voffB); PG8_STAGE(PG8_SA(1, 0), a3, voffA);
;             PG8_WAIT_V(8); PG8_WAIT_L(0); PG8_BAR; PG8_MMA(1, 0, At, B0); PG8_MMA(1, 1, At, B1); PG8_BAR; PG8_SCHED;
.LBB0_69:
	s_add_u32 s6, s4, 0xfffc0080
	s_addc_u32 s7, s5, -1
	s_add_i32 s86, 0, 0x10000
	s_cmp_eq_u32 s85, 12
	s_cselect_b32 s79, s51, s7
	s_cselect_b32 s78, s81, s6
	s_cselect_b32 s7, s49, s84
	s_cselect_b32 s6, s82, s83
	s_add_i32 s88, 0, 0x14000
	v_add_u32_e32 v142, s86, v186
	v_add_u32_e32 v168, s88, v186
	ds_read_b128 v[130:133], v142
	ds_read_b128 v[134:137], v142 offset:1024
	ds_read_b128 v[138:141], v142 offset:2048
	ds_read_b128 v[142:145], v142 offset:3072
	ds_read_b128 v[146:149], v168
	ds_read_b128 v[150:153], v168 offset:1024
	ds_read_b128 v[164:167], v168 offset:2048
	ds_read_b128 v[180:183], v168 offset:3072
	s_add_i32 m0, s12, 0xc000
	ds_read_b128 v[190:193], v188
	ds_read_b128 v[194:197], v188 offset:1024
	ds_read_b128 v[198:201], v188 offset:2048
	ds_read_b128 v[202:205], v188 offset:3072
	ds_read_b128 v[206:209], v188 offset:4096
	ds_read_b128 v[230:233], v188 offset:5120
	ds_read_b128 v[234:237], v188 offset:6144
	ds_read_b128 v[238:241], v188 offset:7168
	global_load_lds_dwordx4 v160, s[4:5]
	s_add_i32 m0, s12, 0xe000
	s_nop 0
	global_load_lds_dwordx4 v162, s[4:5]
	s_waitcnt vmcnt(8)
	s_waitcnt lgkmcnt(0)
	s_barrier
	s_setprio 1
	s_waitcnt lgkmcnt(0)
	v_mfma_f32_16x16x32_bf16 v[126:129], v[130:133], v[190:193], v[126:129]
	v_mfma_f32_16x16x32_bf16 v[122:125], v[138:141], v[190:193], v[122:125]
	v_mfma_f32_16x16x32_bf16 v[110:113], v[130:133], v[198:201], v[110:113]
	v_mfma_f32_16x16x32_bf16 v[106:109], v[138:141], v[198:201], v[106:109]
	v_mfma_f32_16x16x32_bf16 v[98:101], v[130:133], v[206:209], v[98:101]
	v_mfma_f32_16x16x32_bf16 v[90:93], v[138:141], v[206:209], v[90:93]
	v_mfma_f32_16x16x32_bf16 v[82:85], v[130:133], v[234:237], v[82:85]
	v_mfma_f32_16x16x32_bf16 v[74:77], v[138:141], v[234:237], v[74:77]
	v_mfma_f32_16x16x32_bf16 v[126:129], v[134:137], v[194:197], v[126:129]
	v_mfma_f32_16x16x32_bf16 v[122:125], v[142:145], v[194:197], v[122:125]
	v_mfma_f32_16x16x32_bf16 v[110:113], v[134:137], v[202:205], v[110:113]
	v_mfma_f32_16x16x32_bf16 v[106:109], v[142:145], v[202:205], v[106:109]
	v_mfma_f32_16x16x32_bf16 v[98:101], v[134:137], v[230:233], v[98:101]
	v_mfma_f32_16x16x32_bf16 v[90:93], v[142:145], v[230:233], v[90:93]
	v_mfma_f32_16x16x32_bf16 v[82:85], v[134:137], v[238:241], v[82:85]
	v_mfma_f32_16x16x32_bf16 v[74:77], v[142:145], v[238:241], v[74:77]
	s_setprio 0
	s_setprio 1
	v_mfma_f32_16x16x32_bf16 v[118:121], v[146:149], v[190:193], v[118:121]
	v_mfma_f32_16x16x32_bf16 v[114:117], v[164:167], v[190:193], v[114:117]
	v_mfma_f32_16x16x32_bf16 v[102:105], v[146:149], v[198:201], v[102:105]
	v_mfma_f32_16x16x32_bf16 v[94:97], v[164:167], v[198:201], v[94:97]
	v_mfma_f32_16x16x32_bf16 v[86:89], v[146:149], v[206:209], v[86:89]
	v_mfma_f32_16x16x32_bf16 v[78:81], v[164:167], v[206:209], v[78:81]
	v_mfma_f32_16x16x32_bf16 v[70:73], v[146:149], v[234:237], v[70:73]
	v_mfma_f32_16x16x32_bf16 v[66:69], v[164:167], v[234:237], v[66:69]
	v_mfma_f32_16x16x32_bf16 v[118:121], v[150:153], v[194:197], v[118:121]
	v_mfma_f32_16x16x32_bf16 v[114:117], v[180:183], v[194:197], v[114:117]
	v_mfma_f32_16x16x32_bf16 v[102:105], v[150:153], v[202:205], v[102:105]
	v_mfma_f32_16x16x32_bf16 v[94:97], v[180:183], v[202:205], v[94:97]
	v_mfma_f32_16x16x32_bf16 v[86:89], v[150:153], v[230:233], v[86:89]
	v_mfma_f32_16x16x32_bf16 v[78:81], v[180:183], v[230:233], v[78:81]
	v_mfma_f32_16x16x32_bf16 v[70:73], v[150:153], v[238:241], v[70:73]
	v_mfma_f32_16x16x32_bf16 v[66:69], v[180:183], v[238:241], v[66:69]
	s_setprio 0
	s_barrier
	s_add_i32 s86, s86, s8
	v_lshl_add_u64 v[168:169], s[6:7], 0, v[0:1]
	s_mov_b32 m0, s86
	ds_read_b128 v[190:193], v188 offset:16384
	ds_read_b128 v[194:197], v188 offset:17408
	ds_read_b128 v[198:201], v188 offset:18432
	ds_read_b128 v[202:205], v188 offset:19456
	ds_read_b128 v[206:209], v188 offset:20480
	ds_read_b128 v[230:233], v188 offset:21504
	ds_read_b128 v[234:237], v188 offset:22528
	ds_read_b128 v[238:241], v188 offset:23552
	global_load_lds_dwordx4 v[168:169], off
	s_add_i32 m0, s86, 0x2000
	s_add_u32 s86, s6, 0x40000
	v_lshl_add_u64 v[184:185], s[6:7], 0, v[154:155]
	s_addc_u32 s87, s7, 0
	s_add_i32 s88, s88, s8
	global_load_lds_dwordx4 v[184:185], off
	s_mov_b32 m0, s88
	v_lshl_add_u64 v[228:229], s[78:79], 0, v[156:157]
	global_load_lds_dwordx4 v0, s[86:87]
	s_add_i32 m0, s88, 0x2000
	s_nop 0
	global_load_lds_dwordx4 v154, s[86:87]
	v_lshl_add_u64 v[214:215], s[78:79], 0, v[158:159]
	s_mov_b32 m0, s12
	s_nop 0
	global_load_lds_dwordx4 v[214:215], off
	s_mov_b32 m0, s13
	s_nop 0
	global_load_lds_dwordx4 v[228:229], off
	s_waitcnt vmcnt(8)
	s_waitcnt lgkmcnt(0)
	s_barrier
; #define PG8_STAGE(bufoff, gbase, voff) do { _Pragma("unroll") for (int _i = 0; _i < 2; ++_i) \
;         __builtin_amdgcn_global_load_lds((const unsigned*)((const char*)(gbase) + (voff)[_i]), (LAS unsigned*)(lds + (bufoff) + ldsw + _i * 8192), 16, 0, 0); } while (0)
; #define PG8_LDA(dst, b, h) do { _Pragma("unroll") for (int m = 0; m < 4; ++m) _Pragma("unroll") for (int k = 0; k < 2; ++k) dst[m][k] = *(const LAS bf16x8*)(lds + PG8_SA(b, h) + aoff + m * 2048 + k * 1024); } while (0)
; #define PG8_LDB(dst, b, h) do { _Pragma("unroll") for (int n = 0; n < 2; ++n) _Pragma("unroll") for (int k = 0; k < 2; ++k) dst[n][k] = *(const LAS bf16x8*)(lds + PG8_SB(b, h) + boff + n * 2048 + k * 1024); } while (0)
; #define PG8_WAIT_V(n) asm volatile("s_waitcnt vmcnt(" #n ")" ::: "memory")
; #define PG8_WAIT_L(n) asm volatile("s_waitcnt lgkmcnt(" #n ")" ::: "memory")
; template <bool ALIGN_EPI, class Epi, class Sched>
; DEV void gemm_phase(LAS unsigned char* lds, const Gemm g, const Sched& S, const Epi& E) {
;     ...
;         for (int t = 0; t < nt; t += 2) {
;             const bool last = (t == nt - 2);
;             const char* a1 = cA + (size_t)(t + 1) * kstep;
;             const char* a2 = last ? nA : cA + (size_t)(t + 2) * kstep; const char* b2 = last ? nB : cB + (size_t)(t + 2) * kstep;
;             const char* a3 = a2 + kstep; const char* b3 = b2 + kstep;
;             PG8_LDB(B0, 0, 0); PG8_LDB(B1, 0, 1); PG8_SCHED; PG8_LDA(At, 0, 0); PG8_STAGE(PG8_SA(1, 1), a1 + hstepA, voffA);
;             PG8_WAIT_V(8); PG8_WAIT_L(0); PG8_BAR; PG8_MMA(0, 0, At, B0); PG8_MMA(0, 1, At, B1); PG8_BAR; PG8_SCHED;
;             PG8_LDA(At, 0, 1); PG8_STAGE(PG8_SB(0, 0), b2, voffB); PG8_STAGE(PG8_SB(0, 1), b2 + hstep, voffB); PG8_STAGE(PG8_SA(0, 0), a2, voffA);
;             PG8_WAIT_V(8); PG8_WAIT_L(0); PG8_BAR; PG8_MMA(1, 0, At, B0); PG8_MMA(1, 1, At, B1); PG8_BAR; PG8_SCHED;
;             PG8_LDB(B0, 1, 0); PG8_LDB(B1, 1, 1); PG8_SCHED; PG8_LDA(At, 1, 0); PG8_STAGE(PG8_SA(0, 1), a2 + hstepA, voffA);
;             PG8_WAIT_V(8); PG8_WAIT_L(0); PG8_BAR; PG8_MMA(0, 0, At, B0); PG8_MMA(0, 1, At, B1); PG8_BAR; PG8_SCHED;
;             PG8_LDA(At, 1, 1); PG8_STAGE(PG8_SB(1, 0), b3, voffB); PG8_STAGE(PG8_SB(1, 1), b3 + hstep, voffB); PG8_STAGE(PG8_SA(1, 0), a3, voffA);
;             PG8_WAIT_V(8); PG8_WAIT_L(0); PG8_BAR; PG8_MMA(1, 0, At, B0); PG8_MMA(1, 1, At, B1); PG8_BAR; PG8_SCHED;
	s_setprio 1
	s_waitcnt lgkmcnt(0)
	v_mfma_f32_16x16x32_bf16 v[62:65], v[130:133], v[190:193], v[62:65]
	v_mfma_f32_16x16x32_bf16 v[58:61], v[138:141], v[190:193], v[58:61]
	v_mfma_f32_16x16x32_bf16 v[50:53], v[130:133], v[198:201], v[50:53]
	v_mfma_f32_16x16x32_bf16 v[42:45], v[138:141], v[198:201], v[42:45]
	v_mfma_f32_16x16x32_bf16 v[34:37], v[130:133], v[206:209], v[34:37]
	v_mfma_f32_16x16x32_bf16 v[26:29], v[138:141], v[206:209], v[26:29]
	v_mfma_f32_16x16x32_bf16 v[18:21], v[130:133], v[234:237], v[18:21]
	v_mfma_f32_16x16x32_bf16 v[10:13], v[138:141], v[234:237], v[10:13]
	v_mfma_f32_16x16x32_bf16 v[62:65], v[134:137], v[194:197], v[62:65]
	v_mfma_f32_16x16x32_bf16 v[58:61], v[142:145], v[194:197], v[58:61]
	v_mfma_f32_16x16x32_bf16 v[50:53], v[134:137], v[202:205], v[50:53]
	v_mfma_f32_16x16x32_bf16 v[42:45], v[142:145], v[202:205], v[42:45]
	v_mfma_f32_16x16x32_bf16 v[34:37], v[134:137], v[230:233], v[34:37]
	v_mfma_f32_16x16x32_bf16 v[26:29], v[142:145], v[230:233], v[26:29]
	v_mfma_f32_16x16x32_bf16 v[18:21], v[134:137], v[238:241], v[18:21]
	v_mfma_f32_16x16x32_bf16 v[10:13], v[142:145], v[238:241], v[10:13]
	s_setprio 0
	s_setprio 1
	v_mfma_f32_16x16x32_bf16 v[54:57], v[146:149], v[190:193], v[54:57]
	v_mfma_f32_16x16x32_bf16 v[46:49], v[164:167], v[190:193], v[46:49]
	v_mfma_f32_16x16x32_bf16 v[38:41], v[146:149], v[198:201], v[38:41]
	v_mfma_f32_16x16x32_bf16 v[30:33], v[164:167], v[198:201], v[30:33]
	v_mfma_f32_16x16x32_bf16 v[22:25], v[146:149], v[206:209], v[22:25]
	v_mfma_f32_16x16x32_bf16 v[14:17], v[164:167], v[206:209], v[14:17]
	v_mfma_f32_16x16x32_bf16 v[6:9], v[146:149], v[234:237], v[6:9]
	v_mfma_f32_16x16x32_bf16 v[2:5], v[164:167], v[234:237], v[2:5]
	v_mfma_f32_16x16x32_bf16 v[54:57], v[150:153], v[194:197], v[54:57]
	v_mfma_f32_16x16x32_bf16 v[46:49], v[180:183], v[194:197], v[46:49]
	v_mfma_f32_16x16x32_bf16 v[38:41], v[150:153], v[202:205], v[38:41]
	v_mfma_f32_16x16x32_bf16 v[30:33], v[180:183], v[202:205], v[30:33]
	v_mfma_f32_16x16x32_bf16 v[22:25], v[150:153], v[230:233], v[22:25]
	v_mfma_f32_16x16x32_bf16 v[14:17], v[180:183], v[230:233], v[14:17]
	v_mfma_f32_16x16x32_bf16 v[6:9], v[150:153], v[238:241], v[6:9]
	v_mfma_f32_16x16x32_bf16 v[2:5], v[180:183], v[238:241], v[2:5]
	s_setprio 0
	s_barrier
	s_add_i32 s86, 0, 0x18000
	s_add_i32 s87, 0, 0x1c000
	v_add_u32_e32 v142, s86, v186
	v_add_u32_e32 v180, s87, v186
	ds_read_b128 v[130:133], v142
	ds_read_b128 v[134:137], v142 offset:1024
	ds_read_b128 v[138:141], v142 offset:2048
	ds_read_b128 v[142:145], v142 offset:3072
	ds_read_b128 v[146:149], v180
	ds_read_b128 v[150:153], v180 offset:1024
	ds_read_b128 v[164:167], v180 offset:2048
	ds_read_b128 v[180:183], v180 offset:3072
	s_add_u32 s78, s78, 0x40000
	s_addc_u32 s79, s79, 0
	s_mov_b32 m0, s15
	ds_read_b128 v[190:193], v188 offset:32768
	ds_read_b128 v[194:197], v188 offset:33792
	ds_read_b128 v[198:201], v188 offset:34816
	ds_read_b128 v[202:205], v188 offset:35840
	ds_read_b128 v[206:209], v188 offset:36864
	ds_read_b128 v[230:233], v188 offset:37888
	ds_read_b128 v[234:237], v188 offset:38912
	ds_read_b128 v[238:241], v188 offset:39936
	global_load_lds_dwordx4 v158, s[78:79]
	s_mov_b32 m0, s17
	s_nop 0
	global_load_lds_dwordx4 v156, s[78:79]
	s_waitcnt vmcnt(8)
	s_waitcnt lgkmcnt(0)
	s_barrier
	s_setprio 1
	s_waitcnt lgkmcnt(0)
	v_mfma_f32_16x16x32_bf16 v[126:129], v[130:133], v[190:193], v[126:129]
	v_mfma_f32_16x16x32_bf16 v[122:125], v[138:141], v[190:193], v[122:125]
	v_mfma_f32_16x16x32_bf16 v[110:113], v[130:133], v[198:201], v[110:113]
	v_mfma_f32_16x16x32_bf16 v[106:109], v[138:141], v[198:201], v[106:109]
	v_mfma_f32_16x16x32_bf16 v[98:101], v[130:133], v[206:209], v[98:101]
	v_mfma_f32_16x16x32_bf16 v[90:93], v[138:141], v[206:209], v[90:93]
	v_mfma_f32_16x16x32_bf16 v[82:85], v[130:133], v[234:237], v[82:85]
	v_mfma_f32_16x16x32_bf16 v[74:77], v[138:141], v[234:237], v[74:77]
	v_mfma_f32_16x16x32_bf16 v[126:129], v[134:137], v[194:197], v[126:129]
	v_mfma_f32_16x16x32_bf16 v[122:125], v[142:145], v[194:197], v[122:125]
	v_mfma_f32_16x16x32_bf16 v[110:113], v[134:137], v[202:205], v[110:113]
	v_mfma_f32_16x16x32_bf16 v[106:109], v[142:145], v[202:205], v[106:109]
	v_mfma_f32_16x16x32_bf16 v[98:101], v[134:137], v[230:233], v[98:101]
	v_mfma_f32_16x16x32_bf16 v[90:93], v[142:145], v[230:233], v[90:93]
	v_mfma_f32_16x16x32_bf16 v[82:85], v[134:137], v[238:241], v[82:85]
	v_mfma_f32_16x16x32_bf16 v[74:77], v[142:145], v[238:241], v[74:77]
	s_setprio 0
	s_setprio 1
	v_mfma_f32_16x16x32_bf16 v[118:121], v[146:149], v[190:193], v[118:121]
	v_mfma_f32_16x16x32_bf16 v[114:117], v[164:167], v[190:193], v[114:117]
	v_mfma_f32_16x16x32_bf16 v[102:105], v[146:149], v[198:201], v[102:105]
	v_mfma_f32_16x16x32_bf16 v[94:97], v[164:167], v[198:201], v[94:97]
	v_mfma_f32_16x16x32_bf16 v[86:89], v[146:149], v[206:209], v[86:89]
	v_mfma_f32_16x16x32_bf16 v[78:81], v[164:167], v[206:209], v[78:81]
	v_mfma_f32_16x16x32_bf16 v[70:73], v[146:149], v[234:237], v[70:73]
	v_mfma_f32_16x16x32_bf16 v[66:69], v[164:167], v[234:237], v[66:69]
	v_mfma_f32_16x16x32_bf16 v[118:121], v[150:153], v[194:197], v[118:121]
	v_mfma_f32_16x16x32_bf16 v[114:117], v[180:183], v[194:197], v[114:117]
	v_mfma_f32_16x16x32_bf16 v[102:105], v[150:153], v[202:205], v[102:105]
	v_mfma_f32_16x16x32_bf16 v[94:97], v[180:183], v[202:205], v[94:97]
	v_mfma_f32_16x16x32_bf16 v[86:89], v[150:153], v[230:233], v[86:89]
	v_mfma_f32_16x16x32_bf16 v[78:81], v[180:183], v[230:233], v[78:81]
	v_mfma_f32_16x16x32_bf16 v[70:73], v[150:153], v[238:241], v[70:73]
	v_mfma_f32_16x16x32_bf16 v[66:69], v[180:183], v[238:241], v[66:69]
	s_setprio 0
	s_barrier
; #define PG8_STAGE(bufoff, gbase, voff) do { _Pragma("unroll") for (int _i = 0; _i < 2; ++_i) \
;         __builtin_amdgcn_global_load_lds((const unsigned*)((const char*)(gbase) + (voff)[_i]), (LAS unsigned*)(lds + (bufoff) + ldsw + _i * 8192), 16, 0, 0); } while (0)
; #define PG8_LDA(dst, b, h) do { _Pragma("unroll") for (int m = 0; m < 4; ++m) _Pragma("unroll") for (int k = 0; k < 2; ++k) dst[m][k] = *(const LAS bf16x8*)(lds + PG8_SA(b, h) + aoff + m * 2048 + k * 1024); } while (0)
; #define PG8_LDB(dst, b, h) do { _Pragma("unroll") for (int n = 0; n < 2; ++n) _Pragma("unroll") for (int k = 0; k < 2; ++k) dst[n][k] = *(const LAS bf16x8*)(lds + PG8_SB(b, h) + boff + n * 2048 + k * 1024); } while (0)
; #define PG8_WAIT_V(n) asm volatile("s_waitcnt vmcnt(" #n ")" ::: "memory")
; #define PG8_WAIT_L(n) asm volatile("s_waitcnt lgkmcnt(" #n ")" ::: "memory")
; template <bool ALIGN_EPI, class Epi, class Sched>
; DEV void gemm_phase(LAS unsigned char* lds, const Gemm g, const Sched& S, const Epi& E) {
;     ...
;         for (int t = 0; t < nt; t += 2) {
;             const bool last = (t == nt - 2);
;             const char* a1 = cA + (size_t)(t + 1) * kstep;
;             const char* a2 = last ? nA : cA + (size_t)(t + 2) * kstep; const char* b2 = last ? nB : cB + (size_t)(t + 2) * kstep;
;             const char* a3 = a2 + kstep; const char* b3 = b2 + kstep;
;             PG8_LDB(B0, 0, 0); PG8_LDB(B1, 0, 1); PG8_SCHED; PG8_LDA(At, 0, 0); PG8_STAGE(PG8_SA(1, 1), a1 + hstepA, voffA);
;             PG8_WAIT_V(8); PG8_WAIT_L(0); PG8_BAR; PG8_MMA(0, 0, At, B0); PG8_MMA(0, 1, At, B1); PG8_BAR; PG8_SCHED;
;             PG8_LDA(At, 0, 1); PG8_STAGE(PG8_SB(0, 0), b2, voffB); PG8_STAGE(PG8_SB(0, 1), b2 + hstep, voffB); PG8_STAGE(PG8_SA(0, 0), a2, voffA);
;             PG8_WAIT_V(8); PG8_WAIT_L(0); PG8_BAR; PG8_MMA(1, 0, At, B0); PG8_MMA(1, 1, At, B1); PG8_BAR; PG8_SCHED;
;             PG8_LDB(B0, 1, 0); PG8_LDB(B1, 1, 1); PG8_SCHED; PG8_LDA(At, 1, 0); PG8_STAGE(PG8_SA(0, 1), a2 + hstepA, voffA);
;             PG8_WAIT_V(8); PG8_WAIT_L(0); PG8_BAR; PG8_MMA(0, 0, At, B0); PG8_MMA(0, 1, At, B1); PG8_BAR; PG8_SCHED;
;             PG8_LDA(At, 1, 1); PG8_STAGE(PG8_SB(1, 0), b3, voffB); PG8_STAGE(PG8_SB(1, 1), b3 + hstep, voffB); PG8_STAGE(PG8_SA(1, 0), a3, voffA);
;             PG8_WAIT_V(8); PG8_WAIT_L(0); PG8_BAR; PG8_MMA(1, 0, At, B0); PG8_MMA(1, 1, At, B1); PG8_BAR; PG8_SCHED;
	s_add_i32 s78, s86, s8
	v_lshl_add_u64 v[168:169], v[168:169], 0, s[30:31]
	s_mov_b32 m0, s78
	ds_read_b128 v[190:193], v188 offset:49152
	ds_read_b128 v[194:197], v188 offset:50176
	ds_read_b128 v[198:201], v188 offset:51200
	ds_read_b128 v[202:205], v188 offset:52224
	ds_read_b128 v[206:209], v188 offset:53248
	ds_read_b128 v[230:233], v188 offset:54272
	ds_read_b128 v[234:237], v188 offset:55296
	ds_read_b128 v[238:241], v188 offset:56320
	global_load_lds_dwordx4 v[168:169], off
	s_add_i32 m0, s78, 0x2000
	s_add_u32 s6, s6, 0x40080
	v_lshl_add_u64 v[168:169], v[184:185], 0, s[30:31]
	s_addc_u32 s7, s7, 0
	s_add_i32 s78, s87, s8
	global_load_lds_dwordx4 v[168:169], off
	s_mov_b32 m0, s78
	s_nop 0
	global_load_lds_dwordx4 v0, s[6:7]
	s_add_i32 m0, s78, 0x2000
	s_nop 0
	global_load_lds_dwordx4 v154, s[6:7]
	v_lshl_add_u64 v[168:169], v[214:215], 0, s[30:31]
	s_mov_b32 m0, s20
	s_nop 0
	global_load_lds_dwordx4 v[168:169], off
	v_lshl_add_u64 v[168:169], v[228:229], 0, s[30:31]
	s_mov_b32 m0, s21
	s_nop 0
	global_load_lds_dwordx4 v[168:169], off
	s_waitcnt vmcnt(8)
	s_waitcnt lgkmcnt(0)
	s_barrier
	s_setprio 1
	s_waitcnt lgkmcnt(0)
	v_mfma_f32_16x16x32_bf16 v[62:65], v[130:133], v[190:193], v[62:65]
	v_mfma_f32_16x16x32_bf16 v[58:61], v[138:141], v[190:193], v[58:61]
	v_mfma_f32_16x16x32_bf16 v[50:53], v[130:133], v[198:201], v[50:53]
	v_mfma_f32_16x16x32_bf16 v[42:45], v[138:141], v[198:201], v[42:45]
	v_mfma_f32_16x16x32_bf16 v[34:37], v[130:133], v[206:209], v[34:37]
	v_mfma_f32_16x16x32_bf16 v[26:29], v[138:141], v[206:209], v[26:29]
	v_mfma_f32_16x16x32_bf16 v[18:21], v[130:133], v[234:237], v[18:21]
	v_mfma_f32_16x16x32_bf16 v[10:13], v[138:141], v[234:237], v[10:13]
	v_mfma_f32_16x16x32_bf16 v[62:65], v[134:137], v[194:197], v[62:65]
	v_mfma_f32_16x16x32_bf16 v[58:61], v[142:145], v[194:197], v[58:61]
	v_mfma_f32_16x16x32_bf16 v[50:53], v[134:137], v[202:205], v[50:53]
	v_mfma_f32_16x16x32_bf16 v[42:45], v[142:145], v[202:205], v[42:45]
	v_mfma_f32_16x16x32_bf16 v[34:37], v[134:137], v[230:233], v[34:37]
	v_mfma_f32_16x16x32_bf16 v[26:29], v[142:145], v[230:233], v[26:29]
	v_mfma_f32_16x16x32_bf16 v[18:21], v[134:137], v[238:241], v[18:21]
	v_mfma_f32_16x16x32_bf16 v[10:13], v[142:145], v[238:241], v[10:13]
	s_setprio 0
	s_setprio 1
	v_mfma_f32_16x16x32_bf16 v[54:57], v[146:149], v[190:193], v[54:57]
	v_mfma_f32_16x16x32_bf16 v[46:49], v[164:167], v[190:193], v[46:49]
	v_mfma_f32_16x16x32_bf16 v[38:41], v[146:149], v[198:201], v[38:41]
	v_mfma_f32_16x16x32_bf16 v[30:33], v[164:167], v[198:201], v[30:33]
	v_mfma_f32_16x16x32_bf16 v[22:25], v[146:149], v[206:209], v[22:25]
	v_mfma_f32_16x16x32_bf16 v[14:17], v[164:167], v[206:209], v[14:17]
	v_mfma_f32_16x16x32_bf16 v[6:9], v[146:149], v[234:237], v[6:9]
	v_mfma_f32_16x16x32_bf16 v[2:5], v[164:167], v[234:237], v[2:5]
	v_mfma_f32_16x16x32_bf16 v[54:57], v[150:153], v[194:197], v[54:57]
	v_mfma_f32_16x16x32_bf16 v[46:49], v[180:183], v[194:197], v[46:49]
	v_mfma_f32_16x16x32_bf16 v[38:41], v[150:153], v[202:205], v[38:41]
	v_mfma_f32_16x16x32_bf16 v[30:33], v[180:183], v[202:205], v[30:33]
	v_mfma_f32_16x16x32_bf16 v[22:25], v[150:153], v[230:233], v[22:25]
	v_mfma_f32_16x16x32_bf16 v[14:17], v[180:183], v[230:233], v[14:17]
	v_mfma_f32_16x16x32_bf16 v[6:9], v[150:153], v[238:241], v[6:9]
	v_mfma_f32_16x16x32_bf16 v[2:5], v[180:183], v[238:241], v[2:5]
	s_setprio 0
	s_barrier
	s_add_i32 s85, s85, 2
	s_add_u32 s4, s4, 0x100
	s_addc_u32 s5, s5, 0
	s_add_u32 s83, s83, 0x100
	s_addc_u32 s84, s84, 0
	s_cmp_gt_u32 s85, 13
	s_cbranch_scc0 .LBB0_69
	s_and_b64 vcc, exec, s[44:45]
	s_cbranch_vccz .LBB0_72
	s_barrier

; #define PG8_STAGE(bufoff, gbase, voff) do { _Pragma("unroll") for (int _i = 0; _i < 2; ++_i) \
;         __builtin_amdgcn_global_load_lds((const unsigned*)((const char*)(gbase) + (voff)[_i]), (LAS unsigned*)(lds + (bufoff) + ldsw + _i * 8192), 16, 0, 0); } while (0)
; #define PG8_LDA(dst, b, h) do { _Pragma("unroll") for (int m = 0; m < 4; ++m) _Pragma("unroll") for (int k = 0; k < 2; ++k) dst[m][k] = *(const LAS bf16x8*)(lds + PG8_SA(b, h) + aoff + m * 2048 + k * 1024); } while (0)
; #define PG8_LDB(dst, b, h) do { _Pragma("unroll") for (int n = 0; n < 2; ++n) _Pragma("unroll") for (int k = 0; k < 2; ++k) dst[n][k] = *(const LAS bf16x8*)(lds + PG8_SB(b, h) + boff + n * 2048 + k * 1024); } while (0)
; #define PG8_WAIT_V(n) asm volatile("s_waitcnt vmcnt(" #n ")" ::: "memory")
; #define PG8_WAIT_L(n) asm volatile("s_waitcnt lgkmcnt(" #n ")" ::: "memory")
; template <bool ALIGN_EPI, class Epi, class Sched>
; DEV void gemm_phase(LAS unsigned char* lds, const Gemm g, const Sched& S, const Epi& E) {
;     ...
;         for (int t = 0; t < nt; t += 2) {
;             const bool last = (t == nt - 2);
;             const char* a1 = cA + (size_t)(t + 1) * kstep;
;             const char* a2 = last ? nA : cA + (size_t)(t + 2) * kstep; const char* b2 = last ? nB : cB + (size_t)(t + 2) * kstep;
;             const char* a3 = a2 + kstep; const char* b3 = b2 + kstep;
;             PG8_LDB(B0, 0, 0); PG8_LDB(B1, 0, 1); PG8_SCHED; PG8_LDA(At, 0, 0); PG8_STAGE(PG8_SA(1, 1), a1 + hstepA, voffA);
;             PG8_WAIT_V(8); PG8_WAIT_L(0); PG8_BAR; PG8_MMA(0, 0, At, B0); PG8_MMA(0, 1, At, B1); PG8_BAR; PG8_SCHED;
;             PG8_LDA(At, 0, 1); PG8_STAGE(PG8_SB(0, 0), b2, voffB); PG8_STAGE(PG8_SB(0, 1), b2 + hstep, voffB); PG8_STAGE(PG8_SA(0, 0), a2, voffA);
;             PG8_WAIT_V(8); PG8_WAIT_L(0); PG8_BAR; PG8_MMA(1, 0, At, B0); PG8_MMA(1, 1, At, B1); PG8_BAR; PG8_SCHED;
;             PG8_LDB(B0, 1, 0); PG8_LDB(B1, 1, 1); PG8_SCHED; PG8_LDA(At, 1, 0); PG8_STAGE(PG8_SA(0, 1), a2 + hstepA, voffA);
;             PG8_WAIT_V(8); PG8_WAIT_L(0); PG8_BAR; PG8_MMA(0, 0, At, B0); PG8_MMA(0, 1, At, B1); PG8_BAR; PG8_SCHED;
;             PG8_LDA(At, 1, 1); PG8_STAGE(PG8_SB(1, 0), b3, voffB); PG8_STAGE(PG8_SB(1, 1), b3 + hstep, voffB); PG8_STAGE(PG8_SA(1, 0), a3, voffA);
;             PG8_WAIT_V(8); PG8_WAIT_L(0); PG8_BAR; PG8_MMA(1, 0, At, B0); PG8_MMA(1, 1, At, B1); PG8_BAR; PG8_SCHED;
.LBB0_91:
	s_add_u32 s6, s4, 0xfffc0080
	s_addc_u32 s7, s5, -1
	s_add_i32 s85, 0, 0x10000
	s_cmp_eq_u32 s84, 12
	s_cselect_b32 s43, s51, s7
	s_cselect_b32 s42, s80, s6
	v_add_u32_e32 v0, s85, v198
	s_cselect_b32 s7, s53, s83
	s_cselect_b32 s6, s81, s82
	s_add_i32 s88, 0, 0x14000
	ds_read_b128 v[132:135], v0
	ds_read_b128 v[136:139], v0 offset:1024
	ds_read_b128 v[140:143], v0 offset:2048
	ds_read_b128 v[144:147], v0 offset:3072
	v_add_u32_e32 v0, s88, v198
	ds_read_b128 v[148:151], v0
	s_waitcnt lgkmcnt(0)
	ds_read_b128 v[152:155], v0 offset:1024
	ds_read_b128 v[156:159], v0 offset:2048
	ds_read_b128 v[160:163], v0 offset:3072
	s_add_i32 m0, s12, 0xc000
	ds_read_b128 v[164:167], v200
	ds_read_b128 v[190:193], v200 offset:1024
	ds_read_b128 v[194:197], v200 offset:2048
	ds_read_b128 v[202:205], v200 offset:3072
	ds_read_b128 v[206:209], v200 offset:4096
	ds_read_b128 v[230:233], v200 offset:5120
	ds_read_b128 v[234:237], v200 offset:6144
	ds_read_b128 v[238:241], v200 offset:7168
	global_load_lds_dwordx4 v186, s[4:5]
	s_add_i32 m0, s12, 0xe000
	s_nop 0
	global_load_lds_dwordx4 v188, s[4:5]
	s_waitcnt vmcnt(8)
	s_waitcnt lgkmcnt(0)
	s_barrier
	s_setprio 1
	s_waitcnt lgkmcnt(0)
	v_mfma_f32_16x16x32_bf16 v[128:131], v[132:135], v[164:167], v[128:131]
	v_mfma_f32_16x16x32_bf16 v[124:127], v[140:143], v[164:167], v[124:127]
	v_mfma_f32_16x16x32_bf16 v[120:123], v[132:135], v[194:197], v[120:123]
	v_mfma_f32_16x16x32_bf16 v[116:119], v[140:143], v[194:197], v[116:119]
	v_mfma_f32_16x16x32_bf16 v[112:115], v[132:135], v[206:209], v[112:115]
	v_mfma_f32_16x16x32_bf16 v[108:111], v[140:143], v[206:209], v[108:111]
	v_mfma_f32_16x16x32_bf16 v[104:107], v[132:135], v[234:237], v[104:107]
	v_mfma_f32_16x16x32_bf16 v[100:103], v[140:143], v[234:237], v[100:103]
	v_mfma_f32_16x16x32_bf16 v[128:131], v[136:139], v[190:193], v[128:131]
	v_mfma_f32_16x16x32_bf16 v[124:127], v[144:147], v[190:193], v[124:127]
	v_mfma_f32_16x16x32_bf16 v[120:123], v[136:139], v[202:205], v[120:123]
	v_mfma_f32_16x16x32_bf16 v[116:119], v[144:147], v[202:205], v[116:119]
	v_mfma_f32_16x16x32_bf16 v[112:115], v[136:139], v[230:233], v[112:115]
	v_mfma_f32_16x16x32_bf16 v[108:111], v[144:147], v[230:233], v[108:111]
	v_mfma_f32_16x16x32_bf16 v[104:107], v[136:139], v[238:241], v[104:107]
	v_mfma_f32_16x16x32_bf16 v[100:103], v[144:147], v[238:241], v[100:103]
	s_setprio 0
	s_setprio 1
	v_mfma_f32_16x16x32_bf16 v[96:99], v[148:151], v[164:167], v[96:99]
	v_mfma_f32_16x16x32_bf16 v[92:95], v[156:159], v[164:167], v[92:95]
	v_mfma_f32_16x16x32_bf16 v[88:91], v[148:151], v[194:197], v[88:91]
	v_mfma_f32_16x16x32_bf16 v[84:87], v[156:159], v[194:197], v[84:87]
	v_mfma_f32_16x16x32_bf16 v[80:83], v[148:151], v[206:209], v[80:83]
	v_mfma_f32_16x16x32_bf16 v[76:79], v[156:159], v[206:209], v[76:79]
	v_mfma_f32_16x16x32_bf16 v[72:75], v[148:151], v[234:237], v[72:75]
	v_mfma_f32_16x16x32_bf16 v[68:71], v[156:159], v[234:237], v[68:71]
	v_mfma_f32_16x16x32_bf16 v[96:99], v[152:155], v[190:193], v[96:99]
	v_mfma_f32_16x16x32_bf16 v[92:95], v[160:163], v[190:193], v[92:95]
	v_mfma_f32_16x16x32_bf16 v[88:91], v[152:155], v[202:205], v[88:91]
	v_mfma_f32_16x16x32_bf16 v[84:87], v[160:163], v[202:205], v[84:87]
	v_mfma_f32_16x16x32_bf16 v[80:83], v[152:155], v[230:233], v[80:83]
	v_mfma_f32_16x16x32_bf16 v[76:79], v[160:163], v[230:233], v[76:79]
	v_mfma_f32_16x16x32_bf16 v[72:75], v[152:155], v[238:241], v[72:75]
	v_mfma_f32_16x16x32_bf16 v[68:71], v[160:163], v[238:241], v[68:71]
	s_setprio 0
	s_barrier
	s_add_i32 s85, s85, s8
	v_lshl_add_u64 v[214:215], s[6:7], 0, v[182:183]
	s_mov_b32 m0, s85
	ds_read_b128 v[164:167], v200 offset:16384
	ds_read_b128 v[190:193], v200 offset:17408
	ds_read_b128 v[194:197], v200 offset:18432
	ds_read_b128 v[202:205], v200 offset:19456
	ds_read_b128 v[206:209], v200 offset:20480
	ds_read_b128 v[230:233], v200 offset:21504
	ds_read_b128 v[234:237], v200 offset:22528
	ds_read_b128 v[238:241], v200 offset:23552
	global_load_lds_dwordx4 v[214:215], off
	s_add_i32 m0, s85, 0x2000
	s_add_u32 s86, s6, 0x40000
	v_lshl_add_u64 v[228:229], s[6:7], 0, v[168:169]
	s_addc_u32 s87, s7, 0
	s_add_i32 s85, s88, s8
	global_load_lds_dwordx4 v[228:229], off
	s_mov_b32 m0, s85
	v_lshl_add_u64 v[242:243], s[42:43], 0, v[184:185]
	global_load_lds_dwordx4 v182, s[86:87]
	s_add_i32 m0, s85, 0x2000
	v_lshl_add_u64 v[244:245], s[42:43], 0, v[180:181]
	global_load_lds_dwordx4 v168, s[86:87]
	s_mov_b32 m0, s12
	s_nop 0
	global_load_lds_dwordx4 v[242:243], off
	s_mov_b32 m0, s13
	s_nop 0
	global_load_lds_dwordx4 v[244:245], off
	s_waitcnt vmcnt(8)
	s_waitcnt lgkmcnt(0)
	s_barrier
; #define PG8_STAGE(bufoff, gbase, voff) do { _Pragma("unroll") for (int _i = 0; _i < 2; ++_i) \
;         __builtin_amdgcn_global_load_lds((const unsigned*)((const char*)(gbase) + (voff)[_i]), (LAS unsigned*)(lds + (bufoff) + ldsw + _i * 8192), 16, 0, 0); } while (0)
; #define PG8_LDA(dst, b, h) do { _Pragma("unroll") for (int m = 0; m < 4; ++m) _Pragma("unroll") for (int k = 0; k < 2; ++k) dst[m][k] = *(const LAS bf16x8*)(lds + PG8_SA(b, h) + aoff + m * 2048 + k * 1024); } while (0)
; #define PG8_LDB(dst, b, h) do { _Pragma("unroll") for (int n = 0; n < 2; ++n) _Pragma("unroll") for (int k = 0; k < 2; ++k) dst[n][k] = *(const LAS bf16x8*)(lds + PG8_SB(b, h) + boff + n * 2048 + k * 1024); } while (0)
; #define PG8_WAIT_V(n) asm volatile("s_waitcnt vmcnt(" #n ")" ::: "memory")
; #define PG8_WAIT_L(n) asm volatile("s_waitcnt lgkmcnt(" #n ")" ::: "memory")
; template <bool ALIGN_EPI, class Epi, class Sched>
; DEV void gemm_phase(LAS unsigned char* lds, const Gemm g, const Sched& S, const Epi& E) {
;     ...
;         for (int t = 0; t < nt; t += 2) {
;             const bool last = (t == nt - 2);
;             const char* a1 = cA + (size_t)(t + 1) * kstep;
;             const char* a2 = last ? nA : cA + (size_t)(t + 2) * kstep; const char* b2 = last ? nB : cB + (size_t)(t + 2) * kstep;
;             const char* a3 = a2 + kstep; const char* b3 = b2 + kstep;
;             PG8_LDB(B0, 0, 0); PG8_LDB(B1, 0, 1); PG8_SCHED; PG8_LDA(At, 0, 0); PG8_STAGE(PG8_SA(1, 1), a1 + hstepA, voffA);
;             PG8_WAIT_V(8); PG8_WAIT_L(0); PG8_BAR; PG8_MMA(0, 0, At, B0); PG8_MMA(0, 1, At, B1); PG8_BAR; PG8_SCHED;
;             PG8_LDA(At, 0, 1); PG8_STAGE(PG8_SB(0, 0), b2, voffB); PG8_STAGE(PG8_SB(0, 1), b2 + hstep, voffB); PG8_STAGE(PG8_SA(0, 0), a2, voffA);
;             PG8_WAIT_V(8); PG8_WAIT_L(0); PG8_BAR; PG8_MMA(1, 0, At, B0); PG8_MMA(1, 1, At, B1); PG8_BAR; PG8_SCHED;
;             PG8_LDB(B0, 1, 0); PG8_LDB(B1, 1, 1); PG8_SCHED; PG8_LDA(At, 1, 0); PG8_STAGE(PG8_SA(0, 1), a2 + hstepA, voffA);
;             PG8_WAIT_V(8); PG8_WAIT_L(0); PG8_BAR; PG8_MMA(0, 0, At, B0); PG8_MMA(0, 1, At, B1); PG8_BAR; PG8_SCHED;
;             PG8_LDA(At, 1, 1); PG8_STAGE(PG8_SB(1, 0), b3, voffB); PG8_STAGE(PG8_SB(1, 1), b3 + hstep, voffB); PG8_STAGE(PG8_SA(1, 0), a3, voffA);
;             PG8_WAIT_V(8); PG8_WAIT_L(0); PG8_BAR; PG8_MMA(1, 0, At, B0); PG8_MMA(1, 1, At, B1); PG8_BAR; PG8_SCHED;
	s_setprio 1
	s_waitcnt lgkmcnt(0)
	v_mfma_f32_16x16x32_bf16 v[64:67], v[132:135], v[164:167], v[64:67]
	v_mfma_f32_16x16x32_bf16 v[60:63], v[140:143], v[164:167], v[60:63]
	v_mfma_f32_16x16x32_bf16 v[56:59], v[132:135], v[194:197], v[56:59]
	v_mfma_f32_16x16x32_bf16 v[52:55], v[140:143], v[194:197], v[52:55]
	v_mfma_f32_16x16x32_bf16 v[48:51], v[132:135], v[206:209], v[48:51]
	v_mfma_f32_16x16x32_bf16 v[44:47], v[140:143], v[206:209], v[44:47]
	v_mfma_f32_16x16x32_bf16 v[40:43], v[132:135], v[234:237], v[40:43]
	v_mfma_f32_16x16x32_bf16 v[36:39], v[140:143], v[234:237], v[36:39]
	v_mfma_f32_16x16x32_bf16 v[64:67], v[136:139], v[190:193], v[64:67]
	v_mfma_f32_16x16x32_bf16 v[60:63], v[144:147], v[190:193], v[60:63]
	v_mfma_f32_16x16x32_bf16 v[56:59], v[136:139], v[202:205], v[56:59]
	v_mfma_f32_16x16x32_bf16 v[52:55], v[144:147], v[202:205], v[52:55]
	v_mfma_f32_16x16x32_bf16 v[48:51], v[136:139], v[230:233], v[48:51]
	v_mfma_f32_16x16x32_bf16 v[44:47], v[144:147], v[230:233], v[44:47]
	v_mfma_f32_16x16x32_bf16 v[40:43], v[136:139], v[238:241], v[40:43]
	v_mfma_f32_16x16x32_bf16 v[36:39], v[144:147], v[238:241], v[36:39]
	s_setprio 0
	s_setprio 1
	v_mfma_f32_16x16x32_bf16 v[32:35], v[148:151], v[164:167], v[32:35]
	v_mfma_f32_16x16x32_bf16 v[28:31], v[156:159], v[164:167], v[28:31]
	v_mfma_f32_16x16x32_bf16 v[24:27], v[148:151], v[194:197], v[24:27]
	v_mfma_f32_16x16x32_bf16 v[20:23], v[156:159], v[194:197], v[20:23]
	v_mfma_f32_16x16x32_bf16 v[16:19], v[148:151], v[206:209], v[16:19]
	v_mfma_f32_16x16x32_bf16 v[12:15], v[156:159], v[206:209], v[12:15]
	v_mfma_f32_16x16x32_bf16 v[8:11], v[148:151], v[234:237], v[8:11]
	v_mfma_f32_16x16x32_bf16 v[2:5], v[156:159], v[234:237], v[4:7]
	v_mfma_f32_16x16x32_bf16 v[32:35], v[152:155], v[190:193], v[32:35]
	v_mfma_f32_16x16x32_bf16 v[28:31], v[160:163], v[190:193], v[28:31]
	v_mfma_f32_16x16x32_bf16 v[24:27], v[152:155], v[202:205], v[24:27]
	v_mfma_f32_16x16x32_bf16 v[20:23], v[160:163], v[202:205], v[20:23]
	v_mfma_f32_16x16x32_bf16 v[16:19], v[152:155], v[230:233], v[16:19]
	v_mfma_f32_16x16x32_bf16 v[12:15], v[160:163], v[230:233], v[12:15]
	v_mfma_f32_16x16x32_bf16 v[8:11], v[152:155], v[238:241], v[8:11]
	v_mfma_f32_16x16x32_bf16 v[2:5], v[160:163], v[238:241], v[2:5]
	s_setprio 0
	s_barrier
	s_add_i32 s85, 0, 0x18000
	v_add_u32_e32 v0, s85, v198
	s_add_i32 s86, 0, 0x1c000
	ds_read_b128 v[132:135], v0
	ds_read_b128 v[136:139], v0 offset:1024
	ds_read_b128 v[140:143], v0 offset:2048
	ds_read_b128 v[144:147], v0 offset:3072
	v_add_u32_e32 v0, s86, v198
	ds_read_b128 v[148:151], v0
	ds_read_b128 v[152:155], v0 offset:1024
	ds_read_b128 v[156:159], v0 offset:2048
	ds_read_b128 v[160:163], v0 offset:3072
	s_add_u32 s42, s42, 0x40000
	s_addc_u32 s43, s43, 0
	s_mov_b32 m0, s15
	ds_read_b128 v[164:167], v200 offset:32768
	ds_read_b128 v[190:193], v200 offset:33792
	ds_read_b128 v[194:197], v200 offset:34816
	ds_read_b128 v[202:205], v200 offset:35840
	ds_read_b128 v[206:209], v200 offset:36864
	ds_read_b128 v[230:233], v200 offset:37888
	ds_read_b128 v[234:237], v200 offset:38912
	ds_read_b128 v[238:241], v200 offset:39936
	global_load_lds_dwordx4 v184, s[42:43]
	s_mov_b32 m0, s17
	s_nop 0
	global_load_lds_dwordx4 v180, s[42:43]
	s_waitcnt vmcnt(8)
	s_waitcnt lgkmcnt(0)
	s_barrier
	s_setprio 1
	s_waitcnt lgkmcnt(0)
	v_mfma_f32_16x16x32_bf16 v[128:131], v[132:135], v[164:167], v[128:131]
	v_mfma_f32_16x16x32_bf16 v[124:127], v[140:143], v[164:167], v[124:127]
	v_mfma_f32_16x16x32_bf16 v[120:123], v[132:135], v[194:197], v[120:123]
	v_mfma_f32_16x16x32_bf16 v[116:119], v[140:143], v[194:197], v[116:119]
	v_mfma_f32_16x16x32_bf16 v[112:115], v[132:135], v[206:209], v[112:115]
	v_mfma_f32_16x16x32_bf16 v[108:111], v[140:143], v[206:209], v[108:111]
	v_mfma_f32_16x16x32_bf16 v[104:107], v[132:135], v[234:237], v[104:107]
	v_mfma_f32_16x16x32_bf16 v[100:103], v[140:143], v[234:237], v[100:103]
	v_mfma_f32_16x16x32_bf16 v[128:131], v[136:139], v[190:193], v[128:131]
	v_mfma_f32_16x16x32_bf16 v[124:127], v[144:147], v[190:193], v[124:127]
	v_mfma_f32_16x16x32_bf16 v[120:123], v[136:139], v[202:205], v[120:123]
	v_mfma_f32_16x16x32_bf16 v[116:119], v[144:147], v[202:205], v[116:119]
	v_mfma_f32_16x16x32_bf16 v[112:115], v[136:139], v[230:233], v[112:115]
	v_mfma_f32_16x16x32_bf16 v[108:111], v[144:147], v[230:233], v[108:111]
	v_mfma_f32_16x16x32_bf16 v[104:107], v[136:139], v[238:241], v[104:107]
	v_mfma_f32_16x16x32_bf16 v[100:103], v[144:147], v[238:241], v[100:103]
	s_setprio 0
	s_setprio 1
	v_mfma_f32_16x16x32_bf16 v[96:99], v[148:151], v[164:167], v[96:99]
	v_mfma_f32_16x16x32_bf16 v[92:95], v[156:159], v[164:167], v[92:95]
	v_mfma_f32_16x16x32_bf16 v[88:91], v[148:151], v[194:197], v[88:91]
	v_mfma_f32_16x16x32_bf16 v[84:87], v[156:159], v[194:197], v[84:87]
	v_mfma_f32_16x16x32_bf16 v[80:83], v[148:151], v[206:209], v[80:83]
	v_mfma_f32_16x16x32_bf16 v[76:79], v[156:159], v[206:209], v[76:79]
	v_mfma_f32_16x16x32_bf16 v[72:75], v[148:151], v[234:237], v[72:75]
	v_mfma_f32_16x16x32_bf16 v[68:71], v[156:159], v[234:237], v[68:71]
	v_mfma_f32_16x16x32_bf16 v[96:99], v[152:155], v[190:193], v[96:99]
	v_mfma_f32_16x16x32_bf16 v[92:95], v[160:163], v[190:193], v[92:95]
	v_mfma_f32_16x16x32_bf16 v[88:91], v[152:155], v[202:205], v[88:91]
	v_mfma_f32_16x16x32_bf16 v[84:87], v[160:163], v[202:205], v[84:87]
	v_mfma_f32_16x16x32_bf16 v[80:83], v[152:155], v[230:233], v[80:83]
	v_mfma_f32_16x16x32_bf16 v[76:79], v[160:163], v[230:233], v[76:79]
	v_mfma_f32_16x16x32_bf16 v[72:75], v[152:155], v[238:241], v[72:75]
	v_mfma_f32_16x16x32_bf16 v[68:71], v[160:163], v[238:241], v[68:71]
	s_setprio 0
	s_barrier
; #define PG8_STAGE(bufoff, gbase, voff) do { _Pragma("unroll") for (int _i = 0; _i < 2; ++_i) \
;         __builtin_amdgcn_global_load_lds((const unsigned*)((const char*)(gbase) + (voff)[_i]), (LAS unsigned*)(lds + (bufoff) + ldsw + _i * 8192), 16, 0, 0); } while (0)
; #define PG8_LDA(dst, b, h) do { _Pragma("unroll") for (int m = 0; m < 4; ++m) _Pragma("unroll") for (int k = 0; k < 2; ++k) dst[m][k] = *(const LAS bf16x8*)(lds + PG8_SA(b, h) + aoff + m * 2048 + k * 1024); } while (0)
; #define PG8_LDB(dst, b, h) do { _Pragma("unroll") for (int n = 0; n < 2; ++n) _Pragma("unroll") for (int k = 0; k < 2; ++k) dst[n][k] = *(const LAS bf16x8*)(lds + PG8_SB(b, h) + boff + n * 2048 + k * 1024); } while (0)
; #define PG8_WAIT_V(n) asm volatile("s_waitcnt vmcnt(" #n ")" ::: "memory")
; #define PG8_WAIT_L(n) asm volatile("s_waitcnt lgkmcnt(" #n ")" ::: "memory")
; template <bool ALIGN_EPI, class Epi, class Sched>
; DEV void gemm_phase(LAS unsigned char* lds, const Gemm g, const Sched& S, const Epi& E) {
;     ...
;         for (int t = 0; t < nt; t += 2) {
;             const bool last = (t == nt - 2);
;             const char* a1 = cA + (size_t)(t + 1) * kstep;
;             const char* a2 = last ? nA : cA + (size_t)(t + 2) * kstep; const char* b2 = last ? nB : cB + (size_t)(t + 2) * kstep;
;             const char* a3 = a2 + kstep; const char* b3 = b2 + kstep;
;             PG8_LDB(B0, 0, 0); PG8_LDB(B1, 0, 1); PG8_SCHED; PG8_LDA(At, 0, 0); PG8_STAGE(PG8_SA(1, 1), a1 + hstepA, voffA);
;             PG8_WAIT_V(8); PG8_WAIT_L(0); PG8_BAR; PG8_MMA(0, 0, At, B0); PG8_MMA(0, 1, At, B1); PG8_BAR; PG8_SCHED;
;             PG8_LDA(At, 0, 1); PG8_STAGE(PG8_SB(0, 0), b2, voffB); PG8_STAGE(PG8_SB(0, 1), b2 + hstep, voffB); PG8_STAGE(PG8_SA(0, 0), a2, voffA);
;             PG8_WAIT_V(8); PG8_WAIT_L(0); PG8_BAR; PG8_MMA(1, 0, At, B0); PG8_MMA(1, 1, At, B1); PG8_BAR; PG8_SCHED;
;             PG8_LDB(B0, 1, 0); PG8_LDB(B1, 1, 1); PG8_SCHED; PG8_LDA(At, 1, 0); PG8_STAGE(PG8_SA(0, 1), a2 + hstepA, voffA);
;             PG8_WAIT_V(8); PG8_WAIT_L(0); PG8_BAR; PG8_MMA(0, 0, At, B0); PG8_MMA(0, 1, At, B1); PG8_BAR; PG8_SCHED;
;             PG8_LDA(At, 1, 1); PG8_STAGE(PG8_SB(1, 0), b3, voffB); PG8_STAGE(PG8_SB(1, 1), b3 + hstep, voffB); PG8_STAGE(PG8_SA(1, 0), a3, voffA);
;             PG8_WAIT_V(8); PG8_WAIT_L(0); PG8_BAR; PG8_MMA(1, 0, At, B0); PG8_MMA(1, 1, At, B1); PG8_BAR; PG8_SCHED;
	s_add_i32 s42, s85, s8
	v_lshl_add_u64 v[6:7], v[214:215], 0, s[30:31]
	s_mov_b32 m0, s42
	ds_read_b128 v[164:167], v200 offset:49152
	ds_read_b128 v[190:193], v200 offset:50176
	ds_read_b128 v[194:197], v200 offset:51200
	ds_read_b128 v[202:205], v200 offset:52224
	ds_read_b128 v[206:209], v200 offset:53248
	ds_read_b128 v[230:233], v200 offset:54272
	ds_read_b128 v[234:237], v200 offset:55296
	ds_read_b128 v[238:241], v200 offset:56320
	global_load_lds_dwordx4 v[6:7], off
	s_add_i32 m0, s42, 0x2000
	s_add_u32 s6, s6, 0x40080
	v_lshl_add_u64 v[6:7], v[228:229], 0, s[30:31]
	s_addc_u32 s7, s7, 0
	s_add_i32 s42, s86, s8
	global_load_lds_dwordx4 v[6:7], off
	s_mov_b32 m0, s42
	s_nop 0
	global_load_lds_dwordx4 v182, s[6:7]
	s_add_i32 m0, s42, 0x2000
	s_nop 0
	global_load_lds_dwordx4 v168, s[6:7]
	v_lshl_add_u64 v[6:7], v[242:243], 0, s[30:31]
	s_mov_b32 m0, s20
	s_nop 0
	global_load_lds_dwordx4 v[6:7], off
	v_lshl_add_u64 v[6:7], v[244:245], 0, s[30:31]
	s_mov_b32 m0, s21
	s_nop 0
	global_load_lds_dwordx4 v[6:7], off
	s_waitcnt vmcnt(8)
	s_waitcnt lgkmcnt(0)
	s_barrier
	s_setprio 1
	s_waitcnt lgkmcnt(0)
	v_mfma_f32_16x16x32_bf16 v[64:67], v[132:135], v[164:167], v[64:67]
	v_mfma_f32_16x16x32_bf16 v[60:63], v[140:143], v[164:167], v[60:63]
	v_mfma_f32_16x16x32_bf16 v[56:59], v[132:135], v[194:197], v[56:59]
	v_mfma_f32_16x16x32_bf16 v[52:55], v[140:143], v[194:197], v[52:55]
	v_mfma_f32_16x16x32_bf16 v[48:51], v[132:135], v[206:209], v[48:51]
	v_mfma_f32_16x16x32_bf16 v[44:47], v[140:143], v[206:209], v[44:47]
	v_mfma_f32_16x16x32_bf16 v[40:43], v[132:135], v[234:237], v[40:43]
	v_mfma_f32_16x16x32_bf16 v[36:39], v[140:143], v[234:237], v[36:39]
	v_mfma_f32_16x16x32_bf16 v[64:67], v[136:139], v[190:193], v[64:67]
	v_mfma_f32_16x16x32_bf16 v[60:63], v[144:147], v[190:193], v[60:63]
	v_mfma_f32_16x16x32_bf16 v[56:59], v[136:139], v[202:205], v[56:59]
	v_mfma_f32_16x16x32_bf16 v[52:55], v[144:147], v[202:205], v[52:55]
	v_mfma_f32_16x16x32_bf16 v[48:51], v[136:139], v[230:233], v[48:51]
	v_mfma_f32_16x16x32_bf16 v[44:47], v[144:147], v[230:233], v[44:47]
	v_mfma_f32_16x16x32_bf16 v[40:43], v[136:139], v[238:241], v[40:43]
	v_mfma_f32_16x16x32_bf16 v[36:39], v[144:147], v[238:241], v[36:39]
	s_setprio 0
	s_setprio 1
	v_mfma_f32_16x16x32_bf16 v[32:35], v[148:151], v[164:167], v[32:35]
	v_mfma_f32_16x16x32_bf16 v[28:31], v[156:159], v[164:167], v[28:31]
	v_mfma_f32_16x16x32_bf16 v[24:27], v[148:151], v[194:197], v[24:27]
	v_mfma_f32_16x16x32_bf16 v[20:23], v[156:159], v[194:197], v[20:23]
	v_mfma_f32_16x16x32_bf16 v[16:19], v[148:151], v[206:209], v[16:19]
	v_mfma_f32_16x16x32_bf16 v[12:15], v[156:159], v[206:209], v[12:15]
	v_mfma_f32_16x16x32_bf16 v[6:9], v[148:151], v[234:237], v[8:11]
	v_mfma_f32_16x16x32_bf16 v[2:5], v[156:159], v[234:237], v[2:5]
	v_mfma_f32_16x16x32_bf16 v[32:35], v[152:155], v[190:193], v[32:35]
	v_mfma_f32_16x16x32_bf16 v[28:31], v[160:163], v[190:193], v[28:31]
	v_mfma_f32_16x16x32_bf16 v[24:27], v[152:155], v[202:205], v[24:27]
	v_mfma_f32_16x16x32_bf16 v[20:23], v[160:163], v[202:205], v[20:23]
	v_mfma_f32_16x16x32_bf16 v[16:19], v[152:155], v[230:233], v[16:19]
	v_mfma_f32_16x16x32_bf16 v[12:15], v[160:163], v[230:233], v[12:15]
	v_mfma_f32_16x16x32_bf16 v[8:11], v[152:155], v[238:241], v[6:9]
	v_mfma_f32_16x16x32_bf16 v[4:7], v[160:163], v[238:241], v[2:5]
	s_setprio 0
	s_barrier
	s_add_i32 s84, s84, 2
	s_add_u32 s4, s4, 0x100
	s_addc_u32 s5, s5, 0
	s_add_u32 s82, s82, 0x100
	s_addc_u32 s83, s83, 0
	s_cmp_gt_u32 s84, 13
	s_cbranch_scc0 .LBB0_91
	s_and_b64 vcc, exec, s[48:49]
	s_cbranch_vccz .LBB0_94
	s_barrier

; #define PG8_STAGE(bufoff, gbase, voff) do { _Pragma("unroll") for (int _i = 0; _i < 2; ++_i) \
;         __builtin_amdgcn_global_load_lds((const unsigned*)((const char*)(gbase) + (voff)[_i]), (LAS unsigned*)(lds + (bufoff) + ldsw + _i * 8192), 16, 0, 0); } while (0)
; #define PG8_LDA(dst, b, h) do { _Pragma("unroll") for (int m = 0; m < 4; ++m) _Pragma("unroll") for (int k = 0; k < 2; ++k) dst[m][k] = *(const LAS bf16x8*)(lds + PG8_SA(b, h) + aoff + m * 2048 + k * 1024); } while (0)
; #define PG8_LDB(dst, b, h) do { _Pragma("unroll") for (int n = 0; n < 2; ++n) _Pragma("unroll") for (int k = 0; k < 2; ++k) dst[n][k] = *(const LAS bf16x8*)(lds + PG8_SB(b, h) + boff + n * 2048 + k * 1024); } while (0)
; #define PG8_WAIT_V(n) asm volatile("s_waitcnt vmcnt(" #n ")" ::: "memory")
; #define PG8_WAIT_L(n) asm volatile("s_waitcnt lgkmcnt(" #n ")" ::: "memory")
; template <bool ALIGN_EPI, class Epi, class Sched>
; DEV void gemm_phase(LAS unsigned char* lds, const Gemm g, const Sched& S, const Epi& E) {
;     ...
;         for (int t = 0; t < nt; t += 2) {
;             const bool last = (t == nt - 2);
;             const char* a1 = cA + (size_t)(t + 1) * kstep;
;             const char* a2 = last ? nA : cA + (size_t)(t + 2) * kstep; const char* b2 = last ? nB : cB + (size_t)(t + 2) * kstep;
;             const char* a3 = a2 + kstep; const char* b3 = b2 + kstep;
;             PG8_LDB(B0, 0, 0); PG8_LDB(B1, 0, 1); PG8_SCHED; PG8_LDA(At, 0, 0); PG8_STAGE(PG8_SA(1, 1), a1 + hstepA, voffA);
;             PG8_WAIT_V(8); PG8_WAIT_L(0); PG8_BAR; PG8_MMA(0, 0, At, B0); PG8_MMA(0, 1, At, B1); PG8_BAR; PG8_SCHED;
;             PG8_LDA(At, 0, 1); PG8_STAGE(PG8_SB(0, 0), b2, voffB); PG8_STAGE(PG8_SB(0, 1), b2 + hstep, voffB); PG8_STAGE(PG8_SA(0, 0), a2, voffA);
;             PG8_WAIT_V(8); PG8_WAIT_L(0); PG8_BAR; PG8_MMA(1, 0, At, B0); PG8_MMA(1, 1, At, B1); PG8_BAR; PG8_SCHED;
;             PG8_LDB(B0, 1, 0); PG8_LDB(B1, 1, 1); PG8_SCHED; PG8_LDA(At, 1, 0); PG8_STAGE(PG8_SA(0, 1), a2 + hstepA, voffA);
;             PG8_WAIT_V(8); PG8_WAIT_L(0); PG8_BAR; PG8_MMA(0, 0, At, B0); PG8_MMA(0, 1, At, B1); PG8_BAR; PG8_SCHED;
;             PG8_LDA(At, 1, 1); PG8_STAGE(PG8_SB(1, 0), b3, voffB); PG8_STAGE(PG8_SB(1, 1), b3 + hstep, voffB); PG8_STAGE(PG8_SA(1, 0), a3, voffA);
;             PG8_WAIT_V(8); PG8_WAIT_L(0); PG8_BAR; PG8_MMA(1, 0, At, B0); PG8_MMA(1, 1, At, B1); PG8_BAR; PG8_SCHED;
.LBB0_315:
	s_add_u32 s6, s4, 0x100
	s_addc_u32 s7, s5, 0
	s_add_i32 s93, 0, 0x10000
	s_cmp_eq_u32 s87, 12
	s_cselect_b32 s95, s17, s7
	s_cselect_b32 s94, s36, s6
	v_add_u32_e32 v0, s93, v171
	s_cselect_b32 s47, s41, s85
	s_cselect_b32 s46, s64, s70
	s_add_i32 vcc_lo, 0, 0x14000
	ds_read_b128 v[130:133], v0
	ds_read_b128 v[134:137], v0 offset:1024
	ds_read_b128 v[138:141], v0 offset:2048
	ds_read_b128 v[142:145], v0 offset:3072
	v_add_u32_e32 v0, vcc_lo, v171
	ds_read_b128 v[146:149], v0
	ds_read_b128 v[150:153], v0 offset:1024
	ds_read_b128 v[154:157], v0 offset:2048
	ds_read_b128 v[158:161], v0 offset:3072
	s_add_i32 m0, s13, 0xc000
	ds_read_b128 v[162:165], v203
	ds_read_b128 v[166:169], v203 offset:1024
	ds_read_b128 v[194:197], v203 offset:2048
	ds_read_b128 v[206:209], v203 offset:3072
	ds_read_b128 v[230:233], v203 offset:4096
	ds_read_b128 v[234:237], v203 offset:5120
	ds_read_b128 v[238:241], v203 offset:6144
	ds_read_b128 v[242:245], v203 offset:7168
	global_load_lds_dwordx4 v190, s[4:5]
	s_add_i32 m0, s13, 0xe000
	s_nop 0
	global_load_lds_dwordx4 v192, s[4:5]
	s_waitcnt vmcnt(8)
	s_waitcnt lgkmcnt(0)
	s_barrier
	s_setprio 1
	s_waitcnt lgkmcnt(0)
	v_mfma_f32_16x16x32_bf16 v[126:129], v[130:133], v[162:165], v[126:129]
	v_mfma_f32_16x16x32_bf16 v[122:125], v[138:141], v[162:165], v[122:125]
	v_mfma_f32_16x16x32_bf16 v[110:113], v[130:133], v[194:197], v[110:113]
	v_mfma_f32_16x16x32_bf16 v[106:109], v[138:141], v[194:197], v[106:109]
	v_mfma_f32_16x16x32_bf16 v[94:97], v[130:133], v[230:233], v[94:97]
	v_mfma_f32_16x16x32_bf16 v[90:93], v[138:141], v[230:233], v[90:93]
	v_mfma_f32_16x16x32_bf16 v[78:81], v[130:133], v[238:241], v[78:81]
	v_mfma_f32_16x16x32_bf16 v[74:77], v[138:141], v[238:241], v[74:77]
	v_mfma_f32_16x16x32_bf16 v[126:129], v[134:137], v[166:169], v[126:129]
	v_mfma_f32_16x16x32_bf16 v[122:125], v[142:145], v[166:169], v[122:125]
	v_mfma_f32_16x16x32_bf16 v[110:113], v[134:137], v[206:209], v[110:113]
	v_mfma_f32_16x16x32_bf16 v[106:109], v[142:145], v[206:209], v[106:109]
	v_mfma_f32_16x16x32_bf16 v[94:97], v[134:137], v[234:237], v[94:97]
	v_mfma_f32_16x16x32_bf16 v[90:93], v[142:145], v[234:237], v[90:93]
	v_mfma_f32_16x16x32_bf16 v[78:81], v[134:137], v[242:245], v[78:81]
	v_mfma_f32_16x16x32_bf16 v[74:77], v[142:145], v[242:245], v[74:77]
	s_setprio 0
	s_setprio 1
	v_mfma_f32_16x16x32_bf16 v[118:121], v[146:149], v[162:165], v[118:121]
	v_mfma_f32_16x16x32_bf16 v[114:117], v[154:157], v[162:165], v[114:117]
	v_mfma_f32_16x16x32_bf16 v[102:105], v[146:149], v[194:197], v[102:105]
	v_mfma_f32_16x16x32_bf16 v[98:101], v[154:157], v[194:197], v[98:101]
	v_mfma_f32_16x16x32_bf16 v[86:89], v[146:149], v[230:233], v[86:89]
	v_mfma_f32_16x16x32_bf16 v[82:85], v[154:157], v[230:233], v[82:85]
	v_mfma_f32_16x16x32_bf16 v[70:73], v[146:149], v[238:241], v[70:73]
	v_mfma_f32_16x16x32_bf16 v[66:69], v[154:157], v[238:241], v[66:69]
	v_mfma_f32_16x16x32_bf16 v[118:121], v[150:153], v[166:169], v[118:121]
	v_mfma_f32_16x16x32_bf16 v[114:117], v[158:161], v[166:169], v[114:117]
	v_mfma_f32_16x16x32_bf16 v[102:105], v[150:153], v[206:209], v[102:105]
	v_mfma_f32_16x16x32_bf16 v[98:101], v[158:161], v[206:209], v[98:101]
	v_mfma_f32_16x16x32_bf16 v[86:89], v[150:153], v[234:237], v[86:89]
	v_mfma_f32_16x16x32_bf16 v[82:85], v[158:161], v[234:237], v[82:85]
	v_mfma_f32_16x16x32_bf16 v[70:73], v[150:153], v[242:245], v[70:73]
	v_mfma_f32_16x16x32_bf16 v[66:69], v[158:161], v[242:245], v[66:69]
	s_setprio 0
	s_barrier
	s_add_i32 s4, s93, s12
	v_lshl_add_u64 v[246:247], s[46:47], 0, v[184:185]
	s_mov_b32 m0, s4
	ds_read_b128 v[162:165], v203 offset:16384
	ds_read_b128 v[166:169], v203 offset:17408
	ds_read_b128 v[194:197], v203 offset:18432
	ds_read_b128 v[206:209], v203 offset:19456
	ds_read_b128 v[230:233], v203 offset:20480
	ds_read_b128 v[234:237], v203 offset:21504
	ds_read_b128 v[238:241], v203 offset:22528
	ds_read_b128 v[242:245], v203 offset:23552
	global_load_lds_dwordx4 v[246:247], off
	s_add_i32 m0, s4, 0x2000
	s_add_u32 s4, s46, 0x40000
	v_lshl_add_u64 v[248:249], s[46:47], 0, v[180:181]
	s_addc_u32 s5, s47, 0
	s_add_i32 s93, vcc_lo, s12
	global_load_lds_dwordx4 v[248:249], off
	s_mov_b32 m0, s93
	v_lshl_add_u64 v[228:229], s[94:95], 0, v[182:183]
	global_load_lds_dwordx4 v184, s[4:5]
	s_add_i32 m0, s93, 0x2000
	s_nop 0
	global_load_lds_dwordx4 v180, s[4:5]
	v_lshl_add_u64 v[250:251], s[94:95], 0, v[186:187]
	s_mov_b32 m0, s13
	s_nop 0
	global_load_lds_dwordx4 v[250:251], off
	s_mov_b32 m0, s15
	s_nop 0
	global_load_lds_dwordx4 v[228:229], off
	s_waitcnt vmcnt(8)
	s_waitcnt lgkmcnt(0)
	s_barrier
; #define PG8_STAGE(bufoff, gbase, voff) do { _Pragma("unroll") for (int _i = 0; _i < 2; ++_i) \
;         __builtin_amdgcn_global_load_lds((const unsigned*)((const char*)(gbase) + (voff)[_i]), (LAS unsigned*)(lds + (bufoff) + ldsw + _i * 8192), 16, 0, 0); } while (0)
; #define PG8_LDA(dst, b, h) do { _Pragma("unroll") for (int m = 0; m < 4; ++m) _Pragma("unroll") for (int k = 0; k < 2; ++k) dst[m][k] = *(const LAS bf16x8*)(lds + PG8_SA(b, h) + aoff + m * 2048 + k * 1024); } while (0)
; #define PG8_LDB(dst, b, h) do { _Pragma("unroll") for (int n = 0; n < 2; ++n) _Pragma("unroll") for (int k = 0; k < 2; ++k) dst[n][k] = *(const LAS bf16x8*)(lds + PG8_SB(b, h) + boff + n * 2048 + k * 1024); } while (0)
; #define PG8_MMA(ai, bj, At, Bt) do { __builtin_amdgcn_s_setprio(1); _Pragma("unroll") for (int m = 0; m < 4; ++m) _Pragma("unroll") for (int n = 0; n < 2; ++n) _Pragma("unroll") for (int k = 0; k < 2; ++k) \
;         acc[ai][bj][m][n] = __builtin_amdgcn_mfma_f32_16x16x32_bf16(Bt[n][k], At[m][k], acc[ai][bj][m][n], 0, 0, 0); __builtin_amdgcn_s_setprio(0); } while (0)
; #define PG8_WAIT_V(n) asm volatile("s_waitcnt vmcnt(" #n ")" ::: "memory")
; #define PG8_WAIT_L(n) asm volatile("s_waitcnt lgkmcnt(" #n ")" ::: "memory")
; #define PG8_BAR __builtin_amdgcn_s_barrier()
; #define PG8_SCHED __builtin_amdgcn_sched_barrier(0)
; template <bool ALIGN_EPI, class Epi, class Sched>
; DEV void gemm_phase(LAS unsigned char* lds, const Gemm g, const Sched& S, const Epi& E) {
;     ...
;             PG8_WAIT_V(8); PG8_WAIT_L(0); PG8_BAR; PG8_MMA(1, 0, At, B0); PG8_MMA(1, 1, At, B1); PG8_BAR; PG8_SCHED;
;             PG8_LDB(B0, 1, 0); PG8_LDB(B1, 1, 1); PG8_SCHED; PG8_LDA(At, 1, 0); PG8_STAGE(PG8_SA(0, 1), a2 + hstepA, voffA);
;             PG8_WAIT_V(8); PG8_WAIT_L(0); PG8_BAR; PG8_MMA(0, 0, At, B0); PG8_MMA(0, 1, At, B1); PG8_BAR; PG8_SCHED;
	s_setprio 1
	s_waitcnt lgkmcnt(0)
	v_mfma_f32_16x16x32_bf16 v[62:65], v[130:133], v[162:165], v[62:65]
	v_mfma_f32_16x16x32_bf16 v[58:61], v[138:141], v[162:165], v[58:61]
	v_mfma_f32_16x16x32_bf16 v[46:49], v[130:133], v[194:197], v[46:49]
	v_mfma_f32_16x16x32_bf16 v[42:45], v[138:141], v[194:197], v[42:45]
	v_mfma_f32_16x16x32_bf16 v[30:33], v[130:133], v[230:233], v[30:33]
	v_mfma_f32_16x16x32_bf16 v[26:29], v[138:141], v[230:233], v[26:29]
	v_mfma_f32_16x16x32_bf16 v[14:17], v[130:133], v[238:241], v[14:17]
	v_mfma_f32_16x16x32_bf16 v[10:13], v[138:141], v[238:241], v[10:13]
	v_mfma_f32_16x16x32_bf16 v[62:65], v[134:137], v[166:169], v[62:65]
	v_mfma_f32_16x16x32_bf16 v[58:61], v[142:145], v[166:169], v[58:61]
	v_mfma_f32_16x16x32_bf16 v[46:49], v[134:137], v[206:209], v[46:49]
	v_mfma_f32_16x16x32_bf16 v[42:45], v[142:145], v[206:209], v[42:45]
	v_mfma_f32_16x16x32_bf16 v[30:33], v[134:137], v[234:237], v[30:33]
	v_mfma_f32_16x16x32_bf16 v[26:29], v[142:145], v[234:237], v[26:29]
	v_mfma_f32_16x16x32_bf16 v[14:17], v[134:137], v[242:245], v[14:17]
	v_mfma_f32_16x16x32_bf16 v[10:13], v[142:145], v[242:245], v[10:13]
	s_setprio 0
	s_setprio 1
	v_mfma_f32_16x16x32_bf16 v[54:57], v[146:149], v[162:165], v[54:57]
	v_mfma_f32_16x16x32_bf16 v[50:53], v[154:157], v[162:165], v[50:53]
	v_mfma_f32_16x16x32_bf16 v[38:41], v[146:149], v[194:197], v[38:41]
	v_mfma_f32_16x16x32_bf16 v[34:37], v[154:157], v[194:197], v[34:37]
	v_mfma_f32_16x16x32_bf16 v[22:25], v[146:149], v[230:233], v[22:25]
	v_mfma_f32_16x16x32_bf16 v[18:21], v[154:157], v[230:233], v[18:21]
	v_mfma_f32_16x16x32_bf16 v[6:9], v[146:149], v[238:241], v[6:9]
	v_mfma_f32_16x16x32_bf16 v[2:5], v[154:157], v[238:241], v[2:5]
	v_mfma_f32_16x16x32_bf16 v[54:57], v[150:153], v[166:169], v[54:57]
	v_mfma_f32_16x16x32_bf16 v[50:53], v[158:161], v[166:169], v[50:53]
	v_mfma_f32_16x16x32_bf16 v[38:41], v[150:153], v[206:209], v[38:41]
	v_mfma_f32_16x16x32_bf16 v[34:37], v[158:161], v[206:209], v[34:37]
	v_mfma_f32_16x16x32_bf16 v[22:25], v[150:153], v[234:237], v[22:25]
	v_mfma_f32_16x16x32_bf16 v[18:21], v[158:161], v[234:237], v[18:21]
	v_mfma_f32_16x16x32_bf16 v[6:9], v[150:153], v[242:245], v[6:9]
	v_mfma_f32_16x16x32_bf16 v[2:5], v[158:161], v[242:245], v[2:5]
	s_setprio 0
	s_barrier
	s_add_i32 s93, 0, 0x18000
	v_add_u32_e32 v0, s93, v171
	s_add_i32 vcc_lo, 0, 0x1c000
	ds_read_b128 v[130:133], v0
	ds_read_b128 v[134:137], v0 offset:1024
	ds_read_b128 v[138:141], v0 offset:2048
	ds_read_b128 v[142:145], v0 offset:3072
	v_add_u32_e32 v0, vcc_lo, v171
	ds_read_b128 v[146:149], v0
	ds_read_b128 v[150:153], v0 offset:1024
	ds_read_b128 v[154:157], v0 offset:2048
	ds_read_b128 v[158:161], v0 offset:3072
	s_add_u32 s4, s94, 0x2000
	s_addc_u32 s5, s95, 0
	s_mov_b32 m0, s20
	ds_read_b128 v[162:165], v203 offset:32768
	ds_read_b128 v[166:169], v203 offset:33792
	ds_read_b128 v[194:197], v203 offset:34816
	ds_read_b128 v[206:209], v203 offset:35840
	ds_read_b128 v[230:233], v203 offset:36864
	ds_read_b128 v[234:237], v203 offset:37888
	ds_read_b128 v[238:241], v203 offset:38912
	ds_read_b128 v[242:245], v203 offset:39936
	global_load_lds_dwordx4 v186, s[4:5]
	s_mov_b32 m0, s21
	s_nop 0
	global_load_lds_dwordx4 v182, s[4:5]
	s_waitcnt vmcnt(8)
	s_waitcnt lgkmcnt(0)
	s_barrier
	s_setprio 1
	s_waitcnt lgkmcnt(0)
	v_mfma_f32_16x16x32_bf16 v[126:129], v[130:133], v[162:165], v[126:129]
	v_mfma_f32_16x16x32_bf16 v[122:125], v[138:141], v[162:165], v[122:125]
	v_mfma_f32_16x16x32_bf16 v[110:113], v[130:133], v[194:197], v[110:113]
	v_mfma_f32_16x16x32_bf16 v[106:109], v[138:141], v[194:197], v[106:109]
	v_mfma_f32_16x16x32_bf16 v[94:97], v[130:133], v[230:233], v[94:97]
	v_mfma_f32_16x16x32_bf16 v[90:93], v[138:141], v[230:233], v[90:93]
	v_mfma_f32_16x16x32_bf16 v[78:81], v[130:133], v[238:241], v[78:81]
	v_mfma_f32_16x16x32_bf16 v[74:77], v[138:141], v[238:241], v[74:77]
	v_mfma_f32_16x16x32_bf16 v[126:129], v[134:137], v[166:169], v[126:129]
	v_mfma_f32_16x16x32_bf16 v[122:125], v[142:145], v[166:169], v[122:125]
	v_mfma_f32_16x16x32_bf16 v[110:113], v[134:137], v[206:209], v[110:113]
	v_mfma_f32_16x16x32_bf16 v[106:109], v[142:145], v[206:209], v[106:109]
	v_mfma_f32_16x16x32_bf16 v[94:97], v[134:137], v[234:237], v[94:97]
	v_mfma_f32_16x16x32_bf16 v[90:93], v[142:145], v[234:237], v[90:93]
	v_mfma_f32_16x16x32_bf16 v[78:81], v[134:137], v[242:245], v[78:81]
	v_mfma_f32_16x16x32_bf16 v[74:77], v[142:145], v[242:245], v[74:77]
	s_setprio 0
	s_setprio 1
	v_mfma_f32_16x16x32_bf16 v[118:121], v[146:149], v[162:165], v[118:121]
	v_mfma_f32_16x16x32_bf16 v[114:117], v[154:157], v[162:165], v[114:117]
	v_mfma_f32_16x16x32_bf16 v[102:105], v[146:149], v[194:197], v[102:105]
	v_mfma_f32_16x16x32_bf16 v[98:101], v[154:157], v[194:197], v[98:101]
	v_mfma_f32_16x16x32_bf16 v[86:89], v[146:149], v[230:233], v[86:89]
	v_mfma_f32_16x16x32_bf16 v[82:85], v[154:157], v[230:233], v[82:85]
	v_mfma_f32_16x16x32_bf16 v[70:73], v[146:149], v[238:241], v[70:73]
	v_mfma_f32_16x16x32_bf16 v[66:69], v[154:157], v[238:241], v[66:69]
	v_mfma_f32_16x16x32_bf16 v[118:121], v[150:153], v[166:169], v[118:121]
	v_mfma_f32_16x16x32_bf16 v[114:117], v[158:161], v[166:169], v[114:117]
	v_mfma_f32_16x16x32_bf16 v[102:105], v[150:153], v[206:209], v[102:105]
	v_mfma_f32_16x16x32_bf16 v[98:101], v[158:161], v[206:209], v[98:101]
	v_mfma_f32_16x16x32_bf16 v[86:89], v[150:153], v[234:237], v[86:89]
	v_mfma_f32_16x16x32_bf16 v[82:85], v[158:161], v[234:237], v[82:85]
	v_mfma_f32_16x16x32_bf16 v[70:73], v[150:153], v[242:245], v[70:73]
	v_mfma_f32_16x16x32_bf16 v[66:69], v[158:161], v[242:245], v[66:69]
	s_setprio 0
	s_barrier
; #define PG8_STAGE(bufoff, gbase, voff) do { _Pragma("unroll") for (int _i = 0; _i < 2; ++_i) \
;         __builtin_amdgcn_global_load_lds((const unsigned*)((const char*)(gbase) + (voff)[_i]), (LAS unsigned*)(lds + (bufoff) + ldsw + _i * 8192), 16, 0, 0); } while (0)
; #define PG8_LDA(dst, b, h) do { _Pragma("unroll") for (int m = 0; m < 4; ++m) _Pragma("unroll") for (int k = 0; k < 2; ++k) dst[m][k] = *(const LAS bf16x8*)(lds + PG8_SA(b, h) + aoff + m * 2048 + k * 1024); } while (0)
; #define PG8_MMA(ai, bj, At, Bt) do { __builtin_amdgcn_s_setprio(1); _Pragma("unroll") for (int m = 0; m < 4; ++m) _Pragma("unroll") for (int n = 0; n < 2; ++n) _Pragma("unroll") for (int k = 0; k < 2; ++k) \
;         acc[ai][bj][m][n] = __builtin_amdgcn_mfma_f32_16x16x32_bf16(Bt[n][k], At[m][k], acc[ai][bj][m][n], 0, 0, 0); __builtin_amdgcn_s_setprio(0); } while (0)
; #define PG8_WAIT_V(n) asm volatile("s_waitcnt vmcnt(" #n ")" ::: "memory")
; #define PG8_WAIT_L(n) asm volatile("s_waitcnt lgkmcnt(" #n ")" ::: "memory")
; #define PG8_BAR __builtin_amdgcn_s_barrier()
; #define PG8_SCHED __builtin_amdgcn_sched_barrier(0)
; template <bool ALIGN_EPI, class Epi, class Sched>
; DEV void gemm_phase(LAS unsigned char* lds, const Gemm g, const Sched& S, const Epi& E) {
;     ...
;             PG8_LDA(At, 1, 1); PG8_STAGE(PG8_SB(1, 0), b3, voffB); PG8_STAGE(PG8_SB(1, 1), b3 + hstep, voffB); PG8_STAGE(PG8_SA(1, 0), a3, voffA);
;             PG8_WAIT_V(8); PG8_WAIT_L(0); PG8_BAR; PG8_MMA(1, 0, At, B0); PG8_MMA(1, 1, At, B1); PG8_BAR; PG8_SCHED;
;         }
;         if (ALIGN_EPI) { if (wr == 0) PG8_BAR; }
	s_add_i32 s4, s93, s12
	v_lshl_add_u64 v[214:215], v[246:247], 0, s[30:31]
	s_mov_b32 m0, s4
	ds_read_b128 v[162:165], v203 offset:49152
	ds_read_b128 v[166:169], v203 offset:50176
	ds_read_b128 v[194:197], v203 offset:51200
	ds_read_b128 v[206:209], v203 offset:52224
	ds_read_b128 v[230:233], v203 offset:53248
	ds_read_b128 v[234:237], v203 offset:54272
	ds_read_b128 v[238:241], v203 offset:55296
	ds_read_b128 v[242:245], v203 offset:56320
	global_load_lds_dwordx4 v[214:215], off
	s_add_i32 m0, s4, 0x2000
	s_add_u32 s4, s46, 0x40080
	v_lshl_add_u64 v[214:215], v[248:249], 0, s[30:31]
	s_addc_u32 s5, s47, 0
	s_add_i32 s46, vcc_lo, s12
	global_load_lds_dwordx4 v[214:215], off
	s_mov_b32 m0, s46
	s_nop 0
	global_load_lds_dwordx4 v184, s[4:5]
	s_add_i32 m0, s46, 0x2000
	s_nop 0
	global_load_lds_dwordx4 v180, s[4:5]
	v_lshl_add_u64 v[214:215], v[250:251], 0, s[30:31]
	s_mov_b32 m0, s78
	s_nop 0
	global_load_lds_dwordx4 v[214:215], off
	v_lshl_add_u64 v[214:215], v[228:229], 0, s[30:31]
	s_mov_b32 m0, s79
	s_nop 0
	global_load_lds_dwordx4 v[214:215], off
	s_waitcnt vmcnt(8)
	s_waitcnt lgkmcnt(0)
	s_barrier
	s_setprio 1
	s_waitcnt lgkmcnt(0)
	v_mfma_f32_16x16x32_bf16 v[62:65], v[130:133], v[162:165], v[62:65]
	v_mfma_f32_16x16x32_bf16 v[58:61], v[138:141], v[162:165], v[58:61]
	v_mfma_f32_16x16x32_bf16 v[46:49], v[130:133], v[194:197], v[46:49]
	v_mfma_f32_16x16x32_bf16 v[42:45], v[138:141], v[194:197], v[42:45]
	v_mfma_f32_16x16x32_bf16 v[30:33], v[130:133], v[230:233], v[30:33]
	v_mfma_f32_16x16x32_bf16 v[26:29], v[138:141], v[230:233], v[26:29]
	v_mfma_f32_16x16x32_bf16 v[14:17], v[130:133], v[238:241], v[14:17]
	v_mfma_f32_16x16x32_bf16 v[10:13], v[138:141], v[238:241], v[10:13]
	v_mfma_f32_16x16x32_bf16 v[62:65], v[134:137], v[166:169], v[62:65]
	v_mfma_f32_16x16x32_bf16 v[58:61], v[142:145], v[166:169], v[58:61]
	v_mfma_f32_16x16x32_bf16 v[46:49], v[134:137], v[206:209], v[46:49]
	v_mfma_f32_16x16x32_bf16 v[42:45], v[142:145], v[206:209], v[42:45]
	v_mfma_f32_16x16x32_bf16 v[30:33], v[134:137], v[234:237], v[30:33]
	v_mfma_f32_16x16x32_bf16 v[26:29], v[142:145], v[234:237], v[26:29]
	v_mfma_f32_16x16x32_bf16 v[14:17], v[134:137], v[242:245], v[14:17]
	v_mfma_f32_16x16x32_bf16 v[10:13], v[142:145], v[242:245], v[10:13]
	s_setprio 0
	s_setprio 1
	v_mfma_f32_16x16x32_bf16 v[54:57], v[146:149], v[162:165], v[54:57]
	v_mfma_f32_16x16x32_bf16 v[50:53], v[154:157], v[162:165], v[50:53]
	v_mfma_f32_16x16x32_bf16 v[38:41], v[146:149], v[194:197], v[38:41]
	v_mfma_f32_16x16x32_bf16 v[34:37], v[154:157], v[194:197], v[34:37]
	v_mfma_f32_16x16x32_bf16 v[22:25], v[146:149], v[230:233], v[22:25]
	v_mfma_f32_16x16x32_bf16 v[18:21], v[154:157], v[230:233], v[18:21]
	v_mfma_f32_16x16x32_bf16 v[6:9], v[146:149], v[238:241], v[6:9]
	v_mfma_f32_16x16x32_bf16 v[2:5], v[154:157], v[238:241], v[2:5]
	v_mfma_f32_16x16x32_bf16 v[54:57], v[150:153], v[166:169], v[54:57]
	v_mfma_f32_16x16x32_bf16 v[50:53], v[158:161], v[166:169], v[50:53]
	v_mfma_f32_16x16x32_bf16 v[38:41], v[150:153], v[206:209], v[38:41]
	v_mfma_f32_16x16x32_bf16 v[34:37], v[158:161], v[206:209], v[34:37]
	v_mfma_f32_16x16x32_bf16 v[22:25], v[150:153], v[234:237], v[22:25]
	v_mfma_f32_16x16x32_bf16 v[18:21], v[158:161], v[234:237], v[18:21]
	v_mfma_f32_16x16x32_bf16 v[6:9], v[150:153], v[242:245], v[6:9]
	v_mfma_f32_16x16x32_bf16 v[2:5], v[158:161], v[242:245], v[2:5]
	s_setprio 0
	s_barrier
	s_add_i32 s87, s87, 2
	s_add_u32 s70, s70, 0x100
	s_addc_u32 s85, s85, 0
	s_cmp_gt_u32 s87, 13
	s_mov_b64 s[4:5], s[6:7]
	s_cbranch_scc0 .LBB0_315
	s_and_b64 vcc, exec, s[54:55]
	s_cbranch_vccz .LBB0_318
	s_barrier

; #define PG8_STAGE(bufoff, gbase, voff) do { _Pragma("unroll") for (int _i = 0; _i < 2; ++_i) \
;         __builtin_amdgcn_global_load_lds((const unsigned*)((const char*)(gbase) + (voff)[_i]), (LAS unsigned*)(lds + (bufoff) + ldsw + _i * 8192), 16, 0, 0); } while (0)
; #define PG8_LDA(dst, b, h) do { _Pragma("unroll") for (int m = 0; m < 4; ++m) _Pragma("unroll") for (int k = 0; k < 2; ++k) dst[m][k] = *(const LAS bf16x8*)(lds + PG8_SA(b, h) + aoff + m * 2048 + k * 1024); } while (0)
; #define PG8_LDB(dst, b, h) do { _Pragma("unroll") for (int n = 0; n < 2; ++n) _Pragma("unroll") for (int k = 0; k < 2; ++k) dst[n][k] = *(const LAS bf16x8*)(lds + PG8_SB(b, h) + boff + n * 2048 + k * 1024); } while (0)
; #define PG8_MMA(ai, bj, At, Bt) do { __builtin_amdgcn_s_setprio(1); _Pragma("unroll") for (int m = 0; m < 4; ++m) _Pragma("unroll") for (int n = 0; n < 2; ++n) _Pragma("unroll") for (int k = 0; k < 2; ++k) \
;         acc[ai][bj][m][n] = __builtin_amdgcn_mfma_f32_16x16x32_bf16(Bt[n][k], At[m][k], acc[ai][bj][m][n], 0, 0, 0); __builtin_amdgcn_s_setprio(0); } while (0)
; #define PG8_WAIT_V(n) asm volatile("s_waitcnt vmcnt(" #n ")" ::: "memory")
; #define PG8_WAIT_L(n) asm volatile("s_waitcnt lgkmcnt(" #n ")" ::: "memory")
; #define PG8_BAR __builtin_amdgcn_s_barrier()
; #define PG8_SCHED __builtin_amdgcn_sched_barrier(0)
; template <bool ALIGN_EPI, class Epi, class Sched>
; DEV void gemm_phase(LAS unsigned char* lds, const Gemm g, const Sched& S, const Epi& E) {
;     ...
;         for (int t = 0; t < nt; t += 2) {
;             const bool last = (t == nt - 2);
;             const char* a1 = cA + (size_t)(t + 1) * kstep;
;             const char* a2 = last ? nA : cA + (size_t)(t + 2) * kstep; const char* b2 = last ? nB : cB + (size_t)(t + 2) * kstep;
;             const char* a3 = a2 + kstep; const char* b3 = b2 + kstep;
;             PG8_LDB(B0, 0, 0); PG8_LDB(B1, 0, 1); PG8_SCHED; PG8_LDA(At, 0, 0); PG8_STAGE(PG8_SA(1, 1), a1 + hstepA, voffA);
;             PG8_WAIT_V(8); PG8_WAIT_L(0); PG8_BAR; PG8_MMA(0, 0, At, B0); PG8_MMA(0, 1, At, B1); PG8_BAR; PG8_SCHED;
;             PG8_LDA(At, 0, 1); PG8_STAGE(PG8_SB(0, 0), b2, voffB); PG8_STAGE(PG8_SB(0, 1), b2 + hstep, voffB); PG8_STAGE(PG8_SA(0, 0), a2, voffA);
;             PG8_WAIT_V(8); PG8_WAIT_L(0); PG8_BAR; PG8_MMA(1, 0, At, B0); PG8_MMA(1, 1, At, B1); PG8_BAR; PG8_SCHED;
.LBB0_488:
	s_add_u32 s6, s4, 0x100
	s_addc_u32 s7, s5, 0
	s_add_i32 s24, 0, 0x10000
	s_cmp_eq_u32 s80, 44
	s_cselect_b32 s53, s43, s7
	s_cselect_b32 s52, s42, s6
	s_cselect_b32 s51, s49, s79
	s_cselect_b32 s50, s48, s78
	s_add_i32 s25, 0, 0x14000
	v_add_u32_e32 v142, s24, v186
	v_add_u32_e32 v168, s25, v186
	ds_read_b128 v[130:133], v142
	ds_read_b128 v[134:137], v142 offset:1024
	ds_read_b128 v[138:141], v142 offset:2048
	ds_read_b128 v[142:145], v142 offset:3072
	ds_read_b128 v[146:149], v168
	ds_read_b128 v[150:153], v168 offset:1024
	ds_read_b128 v[164:167], v168 offset:2048
	ds_read_b128 v[180:183], v168 offset:3072
	s_add_i32 m0, s15, 0xc000
	ds_read_b128 v[190:193], v188
	ds_read_b128 v[194:197], v188 offset:1024
	ds_read_b128 v[198:201], v188 offset:2048
	ds_read_b128 v[202:205], v188 offset:3072
	ds_read_b128 v[206:209], v188 offset:4096
	ds_read_b128 v[230:233], v188 offset:5120
	ds_read_b128 v[234:237], v188 offset:6144
	ds_read_b128 v[238:241], v188 offset:7168
	global_load_lds_dwordx4 v160, s[4:5]
	s_add_i32 m0, s15, 0xe000
	s_nop 0
	global_load_lds_dwordx4 v162, s[4:5]
	s_waitcnt vmcnt(8)
	s_waitcnt lgkmcnt(0)
	s_barrier
	s_setprio 1
	s_waitcnt lgkmcnt(0)
	v_mfma_f32_16x16x32_bf16 v[126:129], v[130:133], v[190:193], v[126:129]
	v_mfma_f32_16x16x32_bf16 v[122:125], v[138:141], v[190:193], v[122:125]
	v_mfma_f32_16x16x32_bf16 v[110:113], v[130:133], v[198:201], v[110:113]
	v_mfma_f32_16x16x32_bf16 v[106:109], v[138:141], v[198:201], v[106:109]
	v_mfma_f32_16x16x32_bf16 v[98:101], v[130:133], v[206:209], v[98:101]
	v_mfma_f32_16x16x32_bf16 v[90:93], v[138:141], v[206:209], v[90:93]
	v_mfma_f32_16x16x32_bf16 v[82:85], v[130:133], v[234:237], v[82:85]
	v_mfma_f32_16x16x32_bf16 v[74:77], v[138:141], v[234:237], v[74:77]
	v_mfma_f32_16x16x32_bf16 v[126:129], v[134:137], v[194:197], v[126:129]
	v_mfma_f32_16x16x32_bf16 v[122:125], v[142:145], v[194:197], v[122:125]
	v_mfma_f32_16x16x32_bf16 v[110:113], v[134:137], v[202:205], v[110:113]
	v_mfma_f32_16x16x32_bf16 v[106:109], v[142:145], v[202:205], v[106:109]
	v_mfma_f32_16x16x32_bf16 v[98:101], v[134:137], v[230:233], v[98:101]
	v_mfma_f32_16x16x32_bf16 v[90:93], v[142:145], v[230:233], v[90:93]
	v_mfma_f32_16x16x32_bf16 v[82:85], v[134:137], v[238:241], v[82:85]
	v_mfma_f32_16x16x32_bf16 v[74:77], v[142:145], v[238:241], v[74:77]
	s_setprio 0
	s_setprio 1
	v_mfma_f32_16x16x32_bf16 v[118:121], v[146:149], v[190:193], v[118:121]
	v_mfma_f32_16x16x32_bf16 v[114:117], v[164:167], v[190:193], v[114:117]
	v_mfma_f32_16x16x32_bf16 v[102:105], v[146:149], v[198:201], v[102:105]
	v_mfma_f32_16x16x32_bf16 v[94:97], v[164:167], v[198:201], v[94:97]
	v_mfma_f32_16x16x32_bf16 v[86:89], v[146:149], v[206:209], v[86:89]
	v_mfma_f32_16x16x32_bf16 v[78:81], v[164:167], v[206:209], v[78:81]
	v_mfma_f32_16x16x32_bf16 v[70:73], v[146:149], v[234:237], v[70:73]
	v_mfma_f32_16x16x32_bf16 v[66:69], v[164:167], v[234:237], v[66:69]
	v_mfma_f32_16x16x32_bf16 v[118:121], v[150:153], v[194:197], v[118:121]
	v_mfma_f32_16x16x32_bf16 v[114:117], v[180:183], v[194:197], v[114:117]
	v_mfma_f32_16x16x32_bf16 v[102:105], v[150:153], v[202:205], v[102:105]
	v_mfma_f32_16x16x32_bf16 v[94:97], v[180:183], v[202:205], v[94:97]
	v_mfma_f32_16x16x32_bf16 v[86:89], v[150:153], v[230:233], v[86:89]
	v_mfma_f32_16x16x32_bf16 v[78:81], v[180:183], v[230:233], v[78:81]
	v_mfma_f32_16x16x32_bf16 v[70:73], v[150:153], v[238:241], v[70:73]
	v_mfma_f32_16x16x32_bf16 v[66:69], v[180:183], v[238:241], v[66:69]
	s_setprio 0
	s_barrier
	s_add_i32 s4, s24, s13
	v_lshl_add_u64 v[168:169], s[50:51], 0, v[0:1]
	s_mov_b32 m0, s4
	ds_read_b128 v[190:193], v188 offset:16384
	ds_read_b128 v[194:197], v188 offset:17408
	ds_read_b128 v[198:201], v188 offset:18432
	ds_read_b128 v[202:205], v188 offset:19456
	ds_read_b128 v[206:209], v188 offset:20480
	ds_read_b128 v[230:233], v188 offset:21504
	ds_read_b128 v[234:237], v188 offset:22528
	ds_read_b128 v[238:241], v188 offset:23552
	global_load_lds_dwordx4 v[168:169], off
	s_add_i32 m0, s4, 0x2000
	s_add_u32 s4, s50, 0xc0000
	v_lshl_add_u64 v[184:185], s[50:51], 0, v[154:155]
	s_addc_u32 s5, s51, 0
	s_add_i32 s24, s25, s13
	global_load_lds_dwordx4 v[184:185], off
	s_mov_b32 m0, s24
	v_lshl_add_u64 v[228:229], s[52:53], 0, v[156:157]
	global_load_lds_dwordx4 v0, s[4:5]
	s_add_i32 m0, s24, 0x2000
	s_nop 0
	global_load_lds_dwordx4 v154, s[4:5]
	v_lshl_add_u64 v[214:215], s[52:53], 0, v[158:159]
	s_mov_b32 m0, s15
	s_nop 0
	global_load_lds_dwordx4 v[214:215], off
	s_mov_b32 m0, s17
	s_nop 0
	global_load_lds_dwordx4 v[228:229], off
	s_waitcnt vmcnt(8)
	s_waitcnt lgkmcnt(0)
	s_barrier
; #define PG8_STAGE(bufoff, gbase, voff) do { _Pragma("unroll") for (int _i = 0; _i < 2; ++_i) \
;         __builtin_amdgcn_global_load_lds((const unsigned*)((const char*)(gbase) + (voff)[_i]), (LAS unsigned*)(lds + (bufoff) + ldsw + _i * 8192), 16, 0, 0); } while (0)
; #define PG8_LDA(dst, b, h) do { _Pragma("unroll") for (int m = 0; m < 4; ++m) _Pragma("unroll") for (int k = 0; k < 2; ++k) dst[m][k] = *(const LAS bf16x8*)(lds + PG8_SA(b, h) + aoff + m * 2048 + k * 1024); } while (0)
; #define PG8_LDB(dst, b, h) do { _Pragma("unroll") for (int n = 0; n < 2; ++n) _Pragma("unroll") for (int k = 0; k < 2; ++k) dst[n][k] = *(const LAS bf16x8*)(lds + PG8_SB(b, h) + boff + n * 2048 + k * 1024); } while (0)
; #define PG8_MMA(ai, bj, At, Bt) do { __builtin_amdgcn_s_setprio(1); _Pragma("unroll") for (int m = 0; m < 4; ++m) _Pragma("unroll") for (int n = 0; n < 2; ++n) _Pragma("unroll") for (int k = 0; k < 2; ++k) \
;         acc[ai][bj][m][n] = __builtin_amdgcn_mfma_f32_16x16x32_bf16(Bt[n][k], At[m][k], acc[ai][bj][m][n], 0, 0, 0); __builtin_amdgcn_s_setprio(0); } while (0)
; #define PG8_WAIT_V(n) asm volatile("s_waitcnt vmcnt(" #n ")" ::: "memory")
; #define PG8_WAIT_L(n) asm volatile("s_waitcnt lgkmcnt(" #n ")" ::: "memory")
; #define PG8_BAR __builtin_amdgcn_s_barrier()
; #define PG8_SCHED __builtin_amdgcn_sched_barrier(0)
; template <bool ALIGN_EPI, class Epi, class Sched>
; DEV void gemm_phase(LAS unsigned char* lds, const Gemm g, const Sched& S, const Epi& E) {
;     ...
;             PG8_WAIT_V(8); PG8_WAIT_L(0); PG8_BAR; PG8_MMA(1, 0, At, B0); PG8_MMA(1, 1, At, B1); PG8_BAR; PG8_SCHED;
;             PG8_LDB(B0, 1, 0); PG8_LDB(B1, 1, 1); PG8_SCHED; PG8_LDA(At, 1, 0); PG8_STAGE(PG8_SA(0, 1), a2 + hstepA, voffA);
;             PG8_WAIT_V(8); PG8_WAIT_L(0); PG8_BAR; PG8_MMA(0, 0, At, B0); PG8_MMA(0, 1, At, B1); PG8_BAR; PG8_SCHED;
	s_setprio 1
	s_waitcnt lgkmcnt(0)
	v_mfma_f32_16x16x32_bf16 v[62:65], v[130:133], v[190:193], v[62:65]
	v_mfma_f32_16x16x32_bf16 v[58:61], v[138:141], v[190:193], v[58:61]
	v_mfma_f32_16x16x32_bf16 v[50:53], v[130:133], v[198:201], v[50:53]
	v_mfma_f32_16x16x32_bf16 v[42:45], v[138:141], v[198:201], v[42:45]
	v_mfma_f32_16x16x32_bf16 v[34:37], v[130:133], v[206:209], v[34:37]
	v_mfma_f32_16x16x32_bf16 v[26:29], v[138:141], v[206:209], v[26:29]
	v_mfma_f32_16x16x32_bf16 v[18:21], v[130:133], v[234:237], v[18:21]
	v_mfma_f32_16x16x32_bf16 v[10:13], v[138:141], v[234:237], v[10:13]
	v_mfma_f32_16x16x32_bf16 v[62:65], v[134:137], v[194:197], v[62:65]
	v_mfma_f32_16x16x32_bf16 v[58:61], v[142:145], v[194:197], v[58:61]
	v_mfma_f32_16x16x32_bf16 v[50:53], v[134:137], v[202:205], v[50:53]
	v_mfma_f32_16x16x32_bf16 v[42:45], v[142:145], v[202:205], v[42:45]
	v_mfma_f32_16x16x32_bf16 v[34:37], v[134:137], v[230:233], v[34:37]
	v_mfma_f32_16x16x32_bf16 v[26:29], v[142:145], v[230:233], v[26:29]
	v_mfma_f32_16x16x32_bf16 v[18:21], v[134:137], v[238:241], v[18:21]
	v_mfma_f32_16x16x32_bf16 v[10:13], v[142:145], v[238:241], v[10:13]
	s_setprio 0
	s_setprio 1
	v_mfma_f32_16x16x32_bf16 v[54:57], v[146:149], v[190:193], v[54:57]
	v_mfma_f32_16x16x32_bf16 v[46:49], v[164:167], v[190:193], v[46:49]
	v_mfma_f32_16x16x32_bf16 v[38:41], v[146:149], v[198:201], v[38:41]
	v_mfma_f32_16x16x32_bf16 v[30:33], v[164:167], v[198:201], v[30:33]
	v_mfma_f32_16x16x32_bf16 v[22:25], v[146:149], v[206:209], v[22:25]
	v_mfma_f32_16x16x32_bf16 v[14:17], v[164:167], v[206:209], v[14:17]
	v_mfma_f32_16x16x32_bf16 v[6:9], v[146:149], v[234:237], v[6:9]
	v_mfma_f32_16x16x32_bf16 v[2:5], v[164:167], v[234:237], v[2:5]
	v_mfma_f32_16x16x32_bf16 v[54:57], v[150:153], v[194:197], v[54:57]
	v_mfma_f32_16x16x32_bf16 v[46:49], v[180:183], v[194:197], v[46:49]
	v_mfma_f32_16x16x32_bf16 v[38:41], v[150:153], v[202:205], v[38:41]
	v_mfma_f32_16x16x32_bf16 v[30:33], v[180:183], v[202:205], v[30:33]
	v_mfma_f32_16x16x32_bf16 v[22:25], v[150:153], v[230:233], v[22:25]
	v_mfma_f32_16x16x32_bf16 v[14:17], v[180:183], v[230:233], v[14:17]
	v_mfma_f32_16x16x32_bf16 v[6:9], v[150:153], v[238:241], v[6:9]
	v_mfma_f32_16x16x32_bf16 v[2:5], v[180:183], v[238:241], v[2:5]
	s_setprio 0
	s_barrier
	s_add_i32 s24, 0, 0x18000
	s_add_i32 s25, 0, 0x1c000
	v_add_u32_e32 v142, s24, v186
	v_add_u32_e32 v180, s25, v186
	ds_read_b128 v[130:133], v142
	ds_read_b128 v[134:137], v142 offset:1024
	ds_read_b128 v[138:141], v142 offset:2048
	ds_read_b128 v[142:145], v142 offset:3072
	ds_read_b128 v[146:149], v180
	ds_read_b128 v[150:153], v180 offset:1024
	ds_read_b128 v[164:167], v180 offset:2048
	ds_read_b128 v[180:183], v180 offset:3072
	s_add_u32 s4, s52, 0xc0000
	s_addc_u32 s5, s53, 0
	s_mov_b32 m0, s20
	ds_read_b128 v[190:193], v188 offset:32768
	ds_read_b128 v[194:197], v188 offset:33792
	ds_read_b128 v[198:201], v188 offset:34816
	ds_read_b128 v[202:205], v188 offset:35840
	ds_read_b128 v[206:209], v188 offset:36864
	ds_read_b128 v[230:233], v188 offset:37888
	ds_read_b128 v[234:237], v188 offset:38912
	ds_read_b128 v[238:241], v188 offset:39936
	global_load_lds_dwordx4 v158, s[4:5]
	s_mov_b32 m0, s21
	s_nop 0
	global_load_lds_dwordx4 v156, s[4:5]
	s_waitcnt vmcnt(8)
	s_waitcnt lgkmcnt(0)
	s_barrier
	s_setprio 1
	s_waitcnt lgkmcnt(0)
	v_mfma_f32_16x16x32_bf16 v[126:129], v[130:133], v[190:193], v[126:129]
	v_mfma_f32_16x16x32_bf16 v[122:125], v[138:141], v[190:193], v[122:125]
	v_mfma_f32_16x16x32_bf16 v[110:113], v[130:133], v[198:201], v[110:113]
	v_mfma_f32_16x16x32_bf16 v[106:109], v[138:141], v[198:201], v[106:109]
	v_mfma_f32_16x16x32_bf16 v[98:101], v[130:133], v[206:209], v[98:101]
	v_mfma_f32_16x16x32_bf16 v[90:93], v[138:141], v[206:209], v[90:93]
	v_mfma_f32_16x16x32_bf16 v[82:85], v[130:133], v[234:237], v[82:85]
	v_mfma_f32_16x16x32_bf16 v[74:77], v[138:141], v[234:237], v[74:77]
	v_mfma_f32_16x16x32_bf16 v[126:129], v[134:137], v[194:197], v[126:129]
	v_mfma_f32_16x16x32_bf16 v[122:125], v[142:145], v[194:197], v[122:125]
	v_mfma_f32_16x16x32_bf16 v[110:113], v[134:137], v[202:205], v[110:113]
	v_mfma_f32_16x16x32_bf16 v[106:109], v[142:145], v[202:205], v[106:109]
	v_mfma_f32_16x16x32_bf16 v[98:101], v[134:137], v[230:233], v[98:101]
	v_mfma_f32_16x16x32_bf16 v[90:93], v[142:145], v[230:233], v[90:93]
	v_mfma_f32_16x16x32_bf16 v[82:85], v[134:137], v[238:241], v[82:85]
	v_mfma_f32_16x16x32_bf16 v[74:77], v[142:145], v[238:241], v[74:77]
	s_setprio 0
	s_setprio 1
	v_mfma_f32_16x16x32_bf16 v[118:121], v[146:149], v[190:193], v[118:121]
	v_mfma_f32_16x16x32_bf16 v[114:117], v[164:167], v[190:193], v[114:117]
	v_mfma_f32_16x16x32_bf16 v[102:105], v[146:149], v[198:201], v[102:105]
	v_mfma_f32_16x16x32_bf16 v[94:97], v[164:167], v[198:201], v[94:97]
	v_mfma_f32_16x16x32_bf16 v[86:89], v[146:149], v[206:209], v[86:89]
	v_mfma_f32_16x16x32_bf16 v[78:81], v[164:167], v[206:209], v[78:81]
	v_mfma_f32_16x16x32_bf16 v[70:73], v[146:149], v[234:237], v[70:73]
	v_mfma_f32_16x16x32_bf16 v[66:69], v[164:167], v[234:237], v[66:69]
	v_mfma_f32_16x16x32_bf16 v[118:121], v[150:153], v[194:197], v[118:121]
	v_mfma_f32_16x16x32_bf16 v[114:117], v[180:183], v[194:197], v[114:117]
	v_mfma_f32_16x16x32_bf16 v[102:105], v[150:153], v[202:205], v[102:105]
	v_mfma_f32_16x16x32_bf16 v[94:97], v[180:183], v[202:205], v[94:97]
	v_mfma_f32_16x16x32_bf16 v[86:89], v[150:153], v[230:233], v[86:89]
	v_mfma_f32_16x16x32_bf16 v[78:81], v[180:183], v[230:233], v[78:81]
	v_mfma_f32_16x16x32_bf16 v[70:73], v[150:153], v[238:241], v[70:73]
	v_mfma_f32_16x16x32_bf16 v[66:69], v[180:183], v[238:241], v[66:69]
	s_setprio 0
	s_barrier
; #define PG8_STAGE(bufoff, gbase, voff) do { _Pragma("unroll") for (int _i = 0; _i < 2; ++_i) \
;         __builtin_amdgcn_global_load_lds((const unsigned*)((const char*)(gbase) + (voff)[_i]), (LAS unsigned*)(lds + (bufoff) + ldsw + _i * 8192), 16, 0, 0); } while (0)
; #define PG8_LDA(dst, b, h) do { _Pragma("unroll") for (int m = 0; m < 4; ++m) _Pragma("unroll") for (int k = 0; k < 2; ++k) dst[m][k] = *(const LAS bf16x8*)(lds + PG8_SA(b, h) + aoff + m * 2048 + k * 1024); } while (0)
; #define PG8_MMA(ai, bj, At, Bt) do { __builtin_amdgcn_s_setprio(1); _Pragma("unroll") for (int m = 0; m < 4; ++m) _Pragma("unroll") for (int n = 0; n < 2; ++n) _Pragma("unroll") for (int k = 0; k < 2; ++k) \
;         acc[ai][bj][m][n] = __builtin_amdgcn_mfma_f32_16x16x32_bf16(Bt[n][k], At[m][k], acc[ai][bj][m][n], 0, 0, 0); __builtin_amdgcn_s_setprio(0); } while (0)
; #define PG8_WAIT_V(n) asm volatile("s_waitcnt vmcnt(" #n ")" ::: "memory")
; #define PG8_WAIT_L(n) asm volatile("s_waitcnt lgkmcnt(" #n ")" ::: "memory")
; #define PG8_BAR __builtin_amdgcn_s_barrier()
; #define PG8_SCHED __builtin_amdgcn_sched_barrier(0)
; template <bool ALIGN_EPI, class Epi, class Sched>
; DEV void gemm_phase(LAS unsigned char* lds, const Gemm g, const Sched& S, const Epi& E) {
;     ...
;             PG8_LDA(At, 1, 1); PG8_STAGE(PG8_SB(1, 0), b3, voffB); PG8_STAGE(PG8_SB(1, 1), b3 + hstep, voffB); PG8_STAGE(PG8_SA(1, 0), a3, voffA);
;             PG8_WAIT_V(8); PG8_WAIT_L(0); PG8_BAR; PG8_MMA(1, 0, At, B0); PG8_MMA(1, 1, At, B1); PG8_BAR; PG8_SCHED;
;         }
;         if (ALIGN_EPI) { if (wr == 0) PG8_BAR; }
	s_add_i32 s4, s24, s13
	v_lshl_add_u64 v[168:169], v[168:169], 0, s[30:31]
	s_mov_b32 m0, s4
	ds_read_b128 v[190:193], v188 offset:49152
	ds_read_b128 v[194:197], v188 offset:50176
	ds_read_b128 v[198:201], v188 offset:51200
	ds_read_b128 v[202:205], v188 offset:52224
	ds_read_b128 v[206:209], v188 offset:53248
	ds_read_b128 v[230:233], v188 offset:54272
	ds_read_b128 v[234:237], v188 offset:55296
	ds_read_b128 v[238:241], v188 offset:56320
	global_load_lds_dwordx4 v[168:169], off
	s_add_i32 m0, s4, 0x2000
	s_add_u32 s4, s50, 0xc0080
	v_lshl_add_u64 v[168:169], v[184:185], 0, s[30:31]
	s_addc_u32 s5, s51, 0
	s_add_i32 s24, s25, s13
	global_load_lds_dwordx4 v[168:169], off
	s_mov_b32 m0, s24
	s_nop 0
	global_load_lds_dwordx4 v0, s[4:5]
	s_add_i32 m0, s24, 0x2000
	s_nop 0
	global_load_lds_dwordx4 v154, s[4:5]
	v_lshl_add_u64 v[168:169], v[214:215], 0, s[30:31]
	s_mov_b32 m0, s36
	s_nop 0
	global_load_lds_dwordx4 v[168:169], off
	v_lshl_add_u64 v[168:169], v[228:229], 0, s[30:31]
	s_mov_b32 m0, s54
	s_nop 0
	global_load_lds_dwordx4 v[168:169], off
	s_waitcnt vmcnt(8)
	s_waitcnt lgkmcnt(0)
	s_barrier
	s_setprio 1
	s_waitcnt lgkmcnt(0)
	v_mfma_f32_16x16x32_bf16 v[62:65], v[130:133], v[190:193], v[62:65]
	v_mfma_f32_16x16x32_bf16 v[58:61], v[138:141], v[190:193], v[58:61]
	v_mfma_f32_16x16x32_bf16 v[50:53], v[130:133], v[198:201], v[50:53]
	v_mfma_f32_16x16x32_bf16 v[42:45], v[138:141], v[198:201], v[42:45]
	v_mfma_f32_16x16x32_bf16 v[34:37], v[130:133], v[206:209], v[34:37]
	v_mfma_f32_16x16x32_bf16 v[26:29], v[138:141], v[206:209], v[26:29]
	v_mfma_f32_16x16x32_bf16 v[18:21], v[130:133], v[234:237], v[18:21]
	v_mfma_f32_16x16x32_bf16 v[10:13], v[138:141], v[234:237], v[10:13]
	v_mfma_f32_16x16x32_bf16 v[62:65], v[134:137], v[194:197], v[62:65]
	v_mfma_f32_16x16x32_bf16 v[58:61], v[142:145], v[194:197], v[58:61]
	v_mfma_f32_16x16x32_bf16 v[50:53], v[134:137], v[202:205], v[50:53]
	v_mfma_f32_16x16x32_bf16 v[42:45], v[142:145], v[202:205], v[42:45]
	v_mfma_f32_16x16x32_bf16 v[34:37], v[134:137], v[230:233], v[34:37]
	v_mfma_f32_16x16x32_bf16 v[26:29], v[142:145], v[230:233], v[26:29]
	v_mfma_f32_16x16x32_bf16 v[18:21], v[134:137], v[238:241], v[18:21]
	v_mfma_f32_16x16x32_bf16 v[10:13], v[142:145], v[238:241], v[10:13]
	s_setprio 0
	s_setprio 1
	v_mfma_f32_16x16x32_bf16 v[54:57], v[146:149], v[190:193], v[54:57]
	v_mfma_f32_16x16x32_bf16 v[46:49], v[164:167], v[190:193], v[46:49]
	v_mfma_f32_16x16x32_bf16 v[38:41], v[146:149], v[198:201], v[38:41]
	v_mfma_f32_16x16x32_bf16 v[30:33], v[164:167], v[198:201], v[30:33]
	v_mfma_f32_16x16x32_bf16 v[22:25], v[146:149], v[206:209], v[22:25]
	v_mfma_f32_16x16x32_bf16 v[14:17], v[164:167], v[206:209], v[14:17]
	v_mfma_f32_16x16x32_bf16 v[6:9], v[146:149], v[234:237], v[6:9]
	v_mfma_f32_16x16x32_bf16 v[2:5], v[164:167], v[234:237], v[2:5]
	v_mfma_f32_16x16x32_bf16 v[54:57], v[150:153], v[194:197], v[54:57]
	v_mfma_f32_16x16x32_bf16 v[46:49], v[180:183], v[194:197], v[46:49]
	v_mfma_f32_16x16x32_bf16 v[38:41], v[150:153], v[202:205], v[38:41]
	v_mfma_f32_16x16x32_bf16 v[30:33], v[180:183], v[202:205], v[30:33]
	v_mfma_f32_16x16x32_bf16 v[22:25], v[150:153], v[230:233], v[22:25]
	v_mfma_f32_16x16x32_bf16 v[14:17], v[180:183], v[230:233], v[14:17]
	v_mfma_f32_16x16x32_bf16 v[6:9], v[150:153], v[238:241], v[6:9]
	v_mfma_f32_16x16x32_bf16 v[2:5], v[180:183], v[238:241], v[2:5]
	s_setprio 0
	s_barrier
	s_add_i32 s80, s80, 2
	s_add_u32 s78, s78, 0x100
	s_addc_u32 s79, s79, 0
	s_cmp_gt_u32 s80, 45
	s_mov_b64 s[4:5], s[6:7]
	s_cbranch_scc0 .LBB0_488
	s_and_b64 vcc, exec, s[46:47]
	s_cbranch_vccz .LBB0_491
	s_barrier
